# P7 epilogue: per-row rstd cached in VGPRs across units and computed one unit ahead (slots round-trip off the critical path)
# speedup vs baseline: 1.0138x; 1.0138x over previous
; __device__ __forceinline__ int hw_lane() { int l; asm volatile("v_mbcnt_lo_u32_b32 %0, -1, 0\n\tv_mbcnt_hi_u32_b32 %0, -1, %0" : "=v"(l)); return l; }
; #define PG8_LAS __attribute__((address_space(3)))
; #define PG8_STAGE(bufoff, gbase, voff) do { _Pragma("unroll") for (int _i = 0; _i < 2; ++_i) \
;         __builtin_amdgcn_global_load_lds((const unsigned*)((const char*)(gbase) + (voff)[_i]), (PG8_LAS unsigned*)(lds + (bufoff) + ldsw + _i * 8192), 16, 0, 0); } while (0)
; #define PG8_WAIT_V(n) asm volatile("s_waitcnt vmcnt(" #n ")" ::: "memory")
; #define PG8_BAR __builtin_amdgcn_s_barrier()
; #define tid  (fresh_tid_w(wave_s))
; #define lane (hw_lane())
; template <class Epi, class Sched, bool ALIGN_EPI = false, bool SP2 = false>
; __device__ __forceinline__ void gemm_phase(PG8_LAS unsigned char* lds, const Gemm g, const Sched& S, const Epi& E, int wave_in) {
;     int tid_l = (wave_in << 6) | hw_lane(); asm volatile("" : "+v"(tid_l));
;     const int tid = tid_l, wid = __builtin_amdgcn_readfirstlane(tid >> 6), lane = tid & 63, wr = wid >> 2, wc = wid & 3, fr = lane & 15, fq = lane >> 4;
;     const int K = g.K, nt = K / BK;
;     unsigned voffA[2], voffB[2];
; #pragma unroll
;     for (int i = 0; i < 2; ++i) { int R, C; stage_rc(tid * 16 + i * 8192, R, C); const int Rb = Epi::PERM ? ((R & ~31) + perm32(R & 31)) : R;
;         voffA[i] = (unsigned)(R * K + C) * 2u; voffB[i] = (unsigned)(Rb * K + C) * 2u; }
;     const size_t kstep = (size_t)(BK * 2);
;     const size_t hstep = (size_t)HALF * K * 2;
;     const size_t tstep = 2 * hstep;
;     const unsigned ldsw = (unsigned)wid * 1024u;
;     const int aoff = lds_byte(wr * 64 + fr, fq * 8), boff = lds_byte(wc * 32 + fr, fq * 8);
;     ...
;     if constexpr (SP2) {
;         PG8_STAGE(PG8_SB(0, 0), cB, voffB); PG8_STAGE(PG8_SB(0, 1), cB + hstep, voffB); PG8_STAGE(PG8_SA(0, 0), cA, voffA); PG8_STAGE(PG8_SA(0, 1), cA + hstep, voffA);
;         if (wr == 1) PG8_BAR;
;         PG8_WAIT_V(2); PG8_BAR;
;         PG8_STAGE(PG8_SB(1, 0), cB + kstep, voffB); PG8_STAGE(PG8_SA(1, 0), cA + kstep, voffA); PG8_STAGE(PG8_SB(1, 1), cB + hstep + kstep, voffB);
;         PG8_WAIT_V(6); PG8_BAR;
.LBB0_891:
	s_add_u32 s24, s22, 0xf100000
	s_addc_u32 s25, s23, 0
	s_add_u32 s26, s12, 0x5500000
	s_addc_u32 s27, s13, 0
	v_readlane_b32 s12, v255, 37
	s_mul_i32 s8, s12, 0x5800
	s_add_u32 s60, s50, s8
	s_addc_u32 s61, s51, 0
	s_add_u32 s10, s10, 0x5900000
	s_addc_u32 s11, s11, 0
	s_add_u32 s84, s4, 0x6500000
	s_addc_u32 s85, s5, 0
	s_add_u32 s92, s14, 0xb000
	v_readlane_b32 s13, v255, 38
	v_writelane_b32 v255, s10, 37
	s_addc_u32 s93, s15, 0
	s_lshl_b32 s4, s9, 5
	v_writelane_b32 v255, s11, 38
	s_and_b32 s11, s4, 0x60
	s_add_i32 m0, s33, 0x18000
	v_lshl_add_u64 v[6:7], v[6:7], 0, s[88:89]
	s_lshl_b32 s8, s18, 6
	s_lshl_b32 s10, s18, 13
	s_lshl_b32 s12, s11, 7
	s_waitcnt vmcnt(2)
	s_barrier
	global_load_lds_dwordx4 v[6:7], off
	v_lshl_add_u64 v[4:5], v[4:5], 0, s[88:89]
	s_add_i32 m0, s33, 0x1a000
	s_add_i32 s9, s33, 0x8000
	s_add_i32 s96, s33, 0xa000
	global_load_lds_dwordx4 v[4:5], off
	v_lshl_add_u64 v[2:3], v[2:3], 0, s[88:89]
	s_mov_b32 m0, s9
	s_add_u32 s4, s78, 0x40080
	global_load_lds_dwordx4 v[2:3], off
	v_lshl_add_u64 v[0:1], v[0:1], 0, s[88:89]
	s_mov_b32 m0, s96
	s_addc_u32 s5, s79, 0
	global_load_lds_dwordx4 v[0:1], off
	s_add_i32 m0, s33, 0x1c000
	v_lshl_add_u64 v[0:1], s[4:5], 0, v[192:193]
	global_load_lds_dwordx4 v[0:1], off
	v_lshl_add_u64 v[0:1], s[4:5], 0, v[168:169]
	s_add_i32 m0, s33, 0x1e000
	v_and_b32_e32 v206, 15, v8
	global_load_lds_dwordx4 v[0:1], off
	v_bfe_u32 v0, v8, 4, 2
	v_lshlrev_b32_e32 v1, 4, v0
	v_lshlrev_b32_e32 v2, 2, v8
	v_lshl_or_b32 v1, v206, 6, v1
	v_and_b32_e32 v2, 32, v2
	s_cmpk_lt_u32 s19, 0x100
	v_bitop3_b32 v3, v1, s10, v2 bitop3:0xde
	s_cselect_b64 s[94:95], -1, 0
	s_lshl_b32 s10, s18, 11
	s_cmp_gt_i32 s18, 0
	v_cmp_lt_u32_e32 vcc, 13, v206
	v_cmp_gt_u32_e64 s[46:47], 2, v206
	s_cselect_b64 s[4:5], -1, 0
	v_bitop3_b32 v207, v1, s12, v2 bitop3:0xde
	s_and_b64 s[22:23], vcc, s[4:5]
	s_and_b64 s[12:13], s[94:95], s[46:47]
	s_cmp_gt_i32 s18, -2
	s_cselect_b64 s[4:5], -1, 0
	v_lshl_or_b32 v208, v0, 3, s11
	v_add_u32_e32 v210, -14, v206
	s_and_b64 s[82:83], vcc, s[4:5]
	s_add_i32 s4, s10, 0x100
	v_lshlrev_b32_e32 v0, 10, v210
	v_lshlrev_b32_e32 v1, 10, v206
	s_add_i32 s5, s4, 0x22000
	v_lshlrev_b32_e32 v2, 2, v208
	s_add_i32 s4, s4, 0x23000
	v_add3_u32 v211, s5, v0, v2
	v_add3_u32 v212, s4, v0, v2
	v_add3_u32 v0, s5, v1, v2
	v_add_u32_e32 v213, 0xffffc000, v0
	v_add_u32_e32 v214, 0xffffd000, v0
	v_add_u32_e32 v215, 0xffffc010, v0
	v_add_u32_e32 v216, 0xffffc210, v0
	v_add_u32_e32 v217, 0xffffd010, v0
	v_add_u32_e32 v218, 0xffffd210, v0
	v_lshlrev_b32_e32 v0, 14, v9
	v_and_b32_e32 v0, 0xffff8000, v0
	v_lshl_add_u32 v0, v10, 11, v0
	v_and_b32_e32 v1, 1, v9
	v_lshl_or_b32 v0, v1, 6, v0
	v_lshl_add_u32 v174, v11, 1, v0
	v_lshlrev_b32_e32 v0, 14, v13
	v_and_b32_e32 v0, 0xffff8000, v0
	s_waitcnt vmcnt(6)
	v_lshl_add_u32 v0, v12, 11, v0
	v_and_b32_e32 v1, 1, v13
	v_lshl_or_b32 v0, v1, 6, v0
	v_readlane_b32 s4, v255, 10
	v_and_b32_e32 v209, 63, v8
	v_cmp_gt_u32_e64 s[40:41], 14, v206
	s_mov_b32 s97, 0
	v_cmp_eq_u32_e64 s[42:43], 0, v206
	v_cmp_lt_u32_e64 s[44:45], 1, v206
	v_mov_b32_e32 v175, v193
	v_lshl_add_u32 v176, v14, 1, v0
	v_mov_b32_e32 v177, v193
	v_add_u32_e32 v219, 0x100, v3
	v_readlane_b32 s69, v254, 57
	s_mov_b32 s71, s4
	s_barrier
	v_readlane_b32 s5, v255, 11
	s_mov_b32 s101, -1
	s_branch .LBB0_894

; #define PG8_LAS __attribute__((address_space(3)))
;     __device__ __forceinline__ void operator()(const f32x4 (&acc)[2][2][4][2], const Unit& u, int wr, int wc, int fr, int fq) const {
;     ...
;         float rs[2][4];
;         load_rs(slots, u.pm * BM + wr * 64, fr, fq, 1.0f, rs);
;         if (fr >= 14) {
; #pragma unroll
;             for (int ai = 0; ai < 2; ++ai)
; #pragma unroll
;                 for (int bj = 0; bj < 2; ++bj)
; #pragma unroll
;                     for (int n = 0; n < 2; ++n) { const f32x4 x = acc[ai][bj][3][n] * rs[ai][3];
;                         *(PG8_LAS f32x4*)(halo + ((ai * 2 + wr) * 2 + (fr - 14)) * 256 + bj * HALF + lcol + 4 * n) = x;
;                         if (ai == 1 && wr == 1) *(f32x4*)(rawh + (size_t)(u.pm * 2 + (fr - 14)) * FF2 + bj * FF + gcol + 4 * n) = x; }
;         }
;         f32x4 w0[2], w1[2], w2[2], bb[2];
; #pragma unroll
;         for (int bj = 0; bj < 2; ++bj) { const int col = bj * FF + gcol;
;             w0[bj] = *(const f32x4*)(cw + col); w1[bj] = *(const f32x4*)(cw + FF2 + col); w2[bj] = *(const f32x4*)(cw + 2 * FF2 + col); bb[bj] = *(const f32x4*)(cb + col); }
;         asm volatile("s_waitcnt lgkmcnt(0)" ::: "memory"); __builtin_amdgcn_s_barrier(); asm volatile("" ::: "memory");
.LBB0_900:
	v_readlane_b32 s18, v255, 37
	v_readlane_b32 s19, v255, 38
	s_lshl_b32 s5, s71, 8
	s_add_i32 s5, s5, s8
	s_lshl_b32 s11, s71, 1
	s_movk_i32 s29, 0x1600
	s_mov_b32 s100, 0xbfb8aa3b
	s_mov_b32 s79, 0
	v_cmp_eq_u32_e64 s[98:99], 15, v206
	v_lshl_or_b32 v233, s69, 7, v208
	v_lshlrev_b32_e32 v237, 2, v206
	v_lshlrev_b32_e32 v233, 2, v233
	v_or_b32_e32 v239, s5, v206
	v_add_u32_e32 v235, 0x2c00, v233
	global_load_dwordx4 v[128:131], v233, s[14:15]
	global_load_dwordx4 v[132:135], v233, s[16:17]
	global_load_dwordx4 v[136:139], v233, s[92:93]
	global_load_dwordx4 v[140:143], v233, s[60:61]
	global_load_dwordx4 v[144:147], v235, s[14:15]
	global_load_dwordx4 v[148:151], v235, s[16:17]
	global_load_dwordx4 v[152:155], v235, s[92:93]
	global_load_dwordx4 v[156:159], v235, s[60:61]
	v_lshrrev_b32_e32 v243, 1, v233
	v_add_u32_e32 v241, s11, v206
	v_mad_u32_u24 v239, v239, s29, v243
	v_mad_u32_u24 v241, v241, s70, v233
	s_cmp_eq_u32 s101, s71
	v_add_u32_e32 v249, 0x2c00, v241
	s_cbranch_scc1 .Lp7_rsok
	v_or_b32_e32 v229, s5, v209
	v_lshlrev_b32_e32 v229, 6, v229
	v_add_u32_e32 v231, 0x2000, v229
	global_load_dwordx4 v[160:163], v229, s[26:27]
	global_load_dwordx4 v[164:167], v229, s[26:27] offset:16
	global_load_dwordx4 v[178:181], v229, s[26:27] offset:32
	global_load_dwordx4 v[182:185], v229, s[26:27] offset:48
	global_load_dwordx4 v[186:189], v231, s[26:27]
	global_load_dwordx4 v[194:197], v231, s[26:27] offset:16
	global_load_dwordx4 v[198:201], v231, s[26:27] offset:32
	global_load_dwordx4 v[202:205], v231, s[26:27] offset:48
	s_waitcnt vmcnt(0)
	v_pk_add_f32 v[162:163], v[162:163], v[166:167]
	v_pk_add_f32 v[188:189], v[188:189], v[196:197]
	v_pk_add_f32 v[160:161], v[160:161], v[164:165]
	v_pk_add_f32 v[186:187], v[186:187], v[194:195]
	v_pk_add_f32 v[164:165], v[180:181], v[184:185]
	v_pk_add_f32 v[194:195], v[200:201], v[204:205]
	v_pk_add_f32 v[166:167], v[178:179], v[182:183]
	v_pk_add_f32 v[196:197], v[198:199], v[202:203]
	v_pk_add_f32 v[162:163], v[162:163], v[164:165]
	v_pk_add_f32 v[188:189], v[188:189], v[194:195]
	v_pk_add_f32 v[160:161], v[160:161], v[166:167]
	v_pk_add_f32 v[186:187], v[186:187], v[196:197]
	v_add_f32_e32 v160, v160, v161
	v_add_f32_e32 v186, v186, v187
	v_add_f32_e32 v161, v162, v163
	v_add_f32_e32 v187, v188, v189
	v_add_f32_e32 v160, v160, v161
	v_add_f32_e32 v186, v186, v187
	v_fmamk_f32 v160, v160, 0x3a800000, v244
	v_fmamk_f32 v186, v186, 0x3a800000, v244
	v_rsq_f32_e32 v160, v160
	v_rsq_f32_e32 v186, v186
	ds_bpermute_b32 v228, v237, v160
	ds_bpermute_b32 v230, v237, v160 offset:64
	ds_bpermute_b32 v232, v237, v160 offset:128
	ds_bpermute_b32 v234, v237, v160 offset:192
	ds_bpermute_b32 v236, v237, v186
	ds_bpermute_b32 v238, v237, v186 offset:64
	ds_bpermute_b32 v240, v237, v186 offset:128
	ds_bpermute_b32 v248, v237, v186 offset:192
	s_mov_b32 s101, s71
.Lp7_rsok:
	s_waitcnt lgkmcnt(0)
	v_pk_mul_f32 v[100:101], v[100:101], v[234:235] op_sel_hi:[1,0]
	v_pk_mul_f32 v[102:103], v[102:103], v[234:235] op_sel_hi:[1,0]
	v_pk_mul_f32 v[36:37], v[36:37], v[234:235] op_sel_hi:[1,0]
	v_pk_mul_f32 v[38:39], v[38:39], v[234:235] op_sel_hi:[1,0]
	v_pk_mul_f32 v[96:97], v[96:97], v[234:235] op_sel_hi:[1,0]
	v_pk_mul_f32 v[98:99], v[98:99], v[234:235] op_sel_hi:[1,0]
	v_pk_mul_f32 v[32:33], v[32:33], v[234:235] op_sel_hi:[1,0]
	v_pk_mul_f32 v[34:35], v[34:35], v[234:235] op_sel_hi:[1,0]
	v_pk_mul_f32 v[68:69], v[68:69], v[248:249] op_sel_hi:[1,0]
	v_pk_mul_f32 v[70:71], v[70:71], v[248:249] op_sel_hi:[1,0]
	v_pk_mul_f32 v[4:5], v[4:5], v[248:249] op_sel_hi:[1,0]
	v_pk_mul_f32 v[6:7], v[6:7], v[248:249] op_sel_hi:[1,0]
	v_pk_mul_f32 v[64:65], v[64:65], v[248:249] op_sel_hi:[1,0]
	v_pk_mul_f32 v[66:67], v[66:67], v[248:249] op_sel_hi:[1,0]
	v_pk_mul_f32 v[0:1], v[0:1], v[248:249] op_sel_hi:[1,0]
	v_pk_mul_f32 v[2:3], v[2:3], v[248:249] op_sel_hi:[1,0]
	s_mov_b64 s[0:1], exec
	s_andn2_b64 exec, exec, s[40:41]
	ds_write_b128 v211, v[100:103]
	ds_write_b128 v211, v[36:39] offset:16
	ds_write_b128 v211, v[96:99] offset:512
	ds_write_b128 v211, v[32:35] offset:528
	ds_write_b128 v211, v[68:71] offset:4096
	ds_write_b128 v211, v[4:7] offset:4112
	ds_write_b128 v211, v[64:67] offset:4608
	ds_write_b128 v211, v[0:3] offset:4624
	s_mov_b64 exec, s[0:1]
	s_waitcnt lgkmcnt(0)
	s_barrier
	s_and_b64 vcc, exec, s[94:95]
	s_cbranch_vccnz .Lp7_hz0
	ds_read_b128 v[160:163], v213
	ds_read_b128 v[164:167], v213 offset:512
	s_branch .Lp7_hr0

; #define PG8_LAS __attribute__((address_space(3)))
;     __device__ __forceinline__ void operator()(const f32x4 (&acc)[2][2][4][2], const Unit& u, int wr, int wc, int fr, int fq) const {
;     ...
;                     for (int n = 0; n < 2; ++n) { const f32x4 x = acc[ai][bj][3][n] * rs[ai][3];
;                         *(PG8_LAS f32x4*)(halo + ((ai * 2 + wr) * 2 + (fr - 14)) * 256 + bj * HALF + lcol + 4 * n) = x;
;                         if (ai == 1 && wr == 1) *(f32x4*)(rawh + (size_t)(u.pm * 2 + (fr - 14)) * FF2 + bj * FF + gcol + 4 * n) = x; }
;     ...
;             for (int ai = 0; ai < 2; ++ai) {
;                 f32x4 pg[2]; const int pb = ai * 2 + wr - 1;
; #pragma unroll
;                 for (int bj = 0; bj < 2; ++bj) { pg[bj] = (f32x4){0.f, 0.f, 0.f, 0.f};
;                     if (pb >= 0 && fr >= 14) pg[bj] = *(const PG8_LAS f32x4*)(halo + (pb * 2 + (fr - 14)) * 256 + bj * HALF + lcol + 4 * n); }
; #pragma unroll
;                 for (int m = 0; m < 4; ++m) {
;                     f32x4 cur[2], h[2];
; #pragma unroll
;                     for (int bj = 0; bj < 2; ++bj) { cur[bj] = acc[ai][bj][m][n] * rs[ai][m]; f32x4 x1, x2;
; #pragma unroll
;                         for (int e = 0; e < 4; ++e) { const float c1 = dpp_ror1(cur[bj][e]), p1 = dpp_ror1(pg[bj][e]), c2 = dpp_ror2(cur[bj][e]), p2 = dpp_ror2(pg[bj][e]);
;                             x1[e] = fr >= 1 ? c1 : p1; x2[e] = fr >= 2 ? c2 : p2; }
;                         h[bj] = bb[bj] + w0[bj] * x2 + w1[bj] * x1 + w2[bj] * cur[bj]; }
;                     if (ai == 0 && wr == 0 && m == 0 && fr < 2) {
;                         *(f32x4*)(hc0 + (size_t)(u.pm * 2 + fr) * FF2 + gcol + 4 * n) = h[0]; *(f32x4*)(hc0 + (size_t)(u.pm * 2 + fr) * FF2 + FF + gcol + 4 * n) = h[1]; }
;                     f32x4 a;
; #pragma unroll
;                     for (int e = 0; e < 4; ++e) { const float g = h[0][e]; a[e] = g * __builtin_amdgcn_rcpf(1.0f + __builtin_amdgcn_exp2f(-1.4426950408889634f * g)) * h[1][e]; }
;                     const unsigned p0 = cvt_pk_bf16(a[0], a[1]), p1 = cvt_pk_bf16(a[2], a[3]);
;                     if (n == 0) { pk_lo[ai][m][0] = p0; pk_lo[ai][m][1] = p1; }
;                     else { u32x4 w; w.x = pk_lo[ai][m][0]; w.y = pk_lo[ai][m][1]; w.z = p0; w.w = p1;
;                         *(u32x4*)(act + (size_t)(u.pm * BM + ai * HALF + wr * 64 + m * 16 + fr) * FF + gcol) = w; }
.Lp7_hr0:
	ds_read_b128 v[178:181], v214
	ds_read_b128 v[182:185], v214 offset:512
	s_waitcnt vmcnt(0) lgkmcnt(0)
	v_pk_mul_f32 v[124:125], v[124:125], v[228:229] op_sel_hi:[1,0]
	v_pk_mul_f32 v[126:127], v[126:127], v[228:229] op_sel_hi:[1,0]
	v_pk_mul_f32 v[120:121], v[120:121], v[228:229] op_sel_hi:[1,0]
	v_pk_mul_f32 v[122:123], v[122:123], v[228:229] op_sel_hi:[1,0]
	v_pk_fma_f32 v[220:221], v[136:137], v[124:125], v[140:141]
	v_pk_fma_f32 v[222:223], v[138:139], v[126:127], v[142:143]
	v_pk_fma_f32 v[224:225], v[152:153], v[120:121], v[156:157]
	v_pk_fma_f32 v[226:227], v[154:155], v[122:123], v[158:159]
	v_cndmask_b32_e64 v188, v124, v160, s[98:99]
	v_cndmask_b32_e64 v189, v125, v161, s[98:99]
	v_cndmask_b32_e64 v196, v126, v162, s[98:99]
	v_cndmask_b32_e64 v197, v127, v163, s[98:99]
	v_cndmask_b32_e64 v200, v120, v164, s[98:99]
	v_cndmask_b32_e64 v201, v121, v165, s[98:99]
	v_cndmask_b32_e64 v204, v122, v166, s[98:99]
	v_cndmask_b32_e64 v205, v123, v167, s[98:99]
	v_fmac_f32_dpp v220, v188, v132 row_ror:1 row_mask:0xf bank_mask:0xf
	v_fmac_f32_dpp v221, v189, v133 row_ror:1 row_mask:0xf bank_mask:0xf
	v_fmac_f32_dpp v222, v196, v134 row_ror:1 row_mask:0xf bank_mask:0xf
	v_fmac_f32_dpp v223, v197, v135 row_ror:1 row_mask:0xf bank_mask:0xf
	v_fmac_f32_dpp v224, v200, v148 row_ror:1 row_mask:0xf bank_mask:0xf
	v_fmac_f32_dpp v225, v201, v149 row_ror:1 row_mask:0xf bank_mask:0xf
	v_fmac_f32_dpp v226, v204, v150 row_ror:1 row_mask:0xf bank_mask:0xf
	v_fmac_f32_dpp v227, v205, v151 row_ror:1 row_mask:0xf bank_mask:0xf
	v_cndmask_b32_e64 v188, v160, v124, s[40:41]
	v_cndmask_b32_e64 v189, v161, v125, s[40:41]
	v_cndmask_b32_e64 v196, v162, v126, s[40:41]
	v_cndmask_b32_e64 v197, v163, v127, s[40:41]
	v_cndmask_b32_e64 v200, v164, v120, s[40:41]
	v_cndmask_b32_e64 v201, v165, v121, s[40:41]
	v_cndmask_b32_e64 v204, v166, v122, s[40:41]
	v_cndmask_b32_e64 v205, v167, v123, s[40:41]
	v_fmac_f32_dpp v220, v188, v128 row_ror:2 row_mask:0xf bank_mask:0xf
	v_fmac_f32_dpp v221, v189, v129 row_ror:2 row_mask:0xf bank_mask:0xf
	v_fmac_f32_dpp v222, v196, v130 row_ror:2 row_mask:0xf bank_mask:0xf
	v_fmac_f32_dpp v223, v197, v131 row_ror:2 row_mask:0xf bank_mask:0xf
	v_fmac_f32_dpp v224, v200, v144 row_ror:2 row_mask:0xf bank_mask:0xf
	v_fmac_f32_dpp v225, v201, v145 row_ror:2 row_mask:0xf bank_mask:0xf
	v_fmac_f32_dpp v226, v204, v146 row_ror:2 row_mask:0xf bank_mask:0xf
	v_fmac_f32_dpp v227, v205, v147 row_ror:2 row_mask:0xf bank_mask:0xf
	s_and_saveexec_b64 s[0:1], s[12:13]
	global_store_dwordx4 v241, v[220:223], s[84:85]
	global_store_dwordx4 v249, v[224:227], s[84:85]
	s_or_b64 exec, exec, s[0:1]
	v_pk_mul_f32 v[190:191], v[220:221], s[100:101] op_sel_hi:[1,0]
	v_pk_mul_f32 v[250:251], v[222:223], s[100:101] op_sel_hi:[1,0]
	v_exp_f32_e32 v190, v190
	v_exp_f32_e32 v191, v191
	v_exp_f32_e32 v250, v250
	v_exp_f32_e32 v251, v251
	v_pk_mul_f32 v[220:221], v[220:221], v[224:225]
	v_pk_mul_f32 v[222:223], v[222:223], v[226:227]
	v_pk_add_f32 v[190:191], v[190:191], 1.0 op_sel_hi:[1,0]
	v_pk_add_f32 v[250:251], v[250:251], 1.0 op_sel_hi:[1,0]
	v_rcp_f32_e32 v190, v190
	v_rcp_f32_e32 v191, v191
	v_rcp_f32_e32 v250, v250
	v_rcp_f32_e32 v251, v251
	v_pk_mul_f32 v[220:221], v[220:221], v[190:191]
	v_pk_mul_f32 v[222:223], v[222:223], v[250:251]
	v_cvt_pk_bf16_f32 v186, v220, v221
	v_cvt_pk_bf16_f32 v187, v222, v223
	s_and_b64 vcc, exec, s[20:21]
	s_cbranch_vccnz .Lp7_norawh
	s_mov_b64 s[0:1], exec
	s_andn2_b64 exec, exec, s[40:41]
	v_add_u32_e32 v229, s11, v210
	v_mad_u32_u24 v229, v229, s70, v233
	v_add_u32_e32 v231, 0x2c00, v229
	global_store_dwordx4 v229, v[68:71], s[18:19]
	global_store_dwordx4 v229, v[4:7], s[18:19] offset:16
	global_store_dwordx4 v231, v[64:67], s[18:19]
	global_store_dwordx4 v231, v[0:3], s[18:19] offset:16
	s_mov_b64 exec, s[0:1]
.Lp7_norawh:
	v_pk_mul_f32 v[116:117], v[116:117], v[230:231] op_sel_hi:[1,0]
	v_pk_mul_f32 v[118:119], v[118:119], v[230:231] op_sel_hi:[1,0]
	v_pk_mul_f32 v[112:113], v[112:113], v[230:231] op_sel_hi:[1,0]
	v_pk_mul_f32 v[114:115], v[114:115], v[230:231] op_sel_hi:[1,0]
	v_pk_fma_f32 v[220:221], v[136:137], v[116:117], v[140:141]
	v_pk_fma_f32 v[222:223], v[138:139], v[118:119], v[142:143]
	v_pk_fma_f32 v[224:225], v[152:153], v[112:113], v[156:157]
	v_pk_fma_f32 v[226:227], v[154:155], v[114:115], v[158:159]
	v_cndmask_b32_e64 v188, v116, v124, s[98:99]
	v_cndmask_b32_e64 v189, v117, v125, s[98:99]
	v_cndmask_b32_e64 v196, v118, v126, s[98:99]
	v_cndmask_b32_e64 v197, v119, v127, s[98:99]
	v_cndmask_b32_e64 v200, v112, v120, s[98:99]
	v_cndmask_b32_e64 v201, v113, v121, s[98:99]
	v_cndmask_b32_e64 v204, v114, v122, s[98:99]
	v_cndmask_b32_e64 v205, v115, v123, s[98:99]
	v_fmac_f32_dpp v220, v188, v132 row_ror:1 row_mask:0xf bank_mask:0xf
	v_fmac_f32_dpp v221, v189, v133 row_ror:1 row_mask:0xf bank_mask:0xf
	v_fmac_f32_dpp v222, v196, v134 row_ror:1 row_mask:0xf bank_mask:0xf
	v_fmac_f32_dpp v223, v197, v135 row_ror:1 row_mask:0xf bank_mask:0xf
	v_fmac_f32_dpp v224, v200, v148 row_ror:1 row_mask:0xf bank_mask:0xf
	v_fmac_f32_dpp v225, v201, v149 row_ror:1 row_mask:0xf bank_mask:0xf
	v_fmac_f32_dpp v226, v204, v150 row_ror:1 row_mask:0xf bank_mask:0xf
	v_fmac_f32_dpp v227, v205, v151 row_ror:1 row_mask:0xf bank_mask:0xf
	v_cndmask_b32_e64 v188, v124, v116, s[40:41]
	v_cndmask_b32_e64 v189, v125, v117, s[40:41]
	v_cndmask_b32_e64 v196, v126, v118, s[40:41]
	v_cndmask_b32_e64 v197, v127, v119, s[40:41]
	v_cndmask_b32_e64 v200, v120, v112, s[40:41]
	v_cndmask_b32_e64 v201, v121, v113, s[40:41]
	v_cndmask_b32_e64 v204, v122, v114, s[40:41]
	v_cndmask_b32_e64 v205, v123, v115, s[40:41]
; __device__ __forceinline__ unsigned cvt_pk_bf16(float lo, float hi) { unsigned r; asm volatile("v_cvt_pk_bf16_f32 %0, %1, %2" : "=v"(r) : "v"(lo), "v"(hi)); return r; }
; __device__ __forceinline__ float dpp_ror1(float x) { return __int_as_float(__builtin_amdgcn_update_dpp(0, __float_as_int(x), 0x121, 0xf, 0xf, false)); }
; __device__ __forceinline__ float dpp_ror2(float x) { return __int_as_float(__builtin_amdgcn_update_dpp(0, __float_as_int(x), 0x122, 0xf, 0xf, false)); }
;     __device__ __forceinline__ void operator()(const f32x4 (&acc)[2][2][4][2], const Unit& u, int wr, int wc, int fr, int fq) const {
;     ...
;                 for (int m = 0; m < 4; ++m) {
;                     f32x4 cur[2], h[2];
; #pragma unroll
;                     for (int bj = 0; bj < 2; ++bj) { cur[bj] = acc[ai][bj][m][n] * rs[ai][m]; f32x4 x1, x2;
; #pragma unroll
;                         for (int e = 0; e < 4; ++e) { const float c1 = dpp_ror1(cur[bj][e]), p1 = dpp_ror1(pg[bj][e]), c2 = dpp_ror2(cur[bj][e]), p2 = dpp_ror2(pg[bj][e]);
;                             x1[e] = fr >= 1 ? c1 : p1; x2[e] = fr >= 2 ? c2 : p2; }
;                         h[bj] = bb[bj] + w0[bj] * x2 + w1[bj] * x1 + w2[bj] * cur[bj]; }
;                     if (ai == 0 && wr == 0 && m == 0 && fr < 2) {
;                         *(f32x4*)(hc0 + (size_t)(u.pm * 2 + fr) * FF2 + gcol + 4 * n) = h[0]; *(f32x4*)(hc0 + (size_t)(u.pm * 2 + fr) * FF2 + FF + gcol + 4 * n) = h[1]; }
;                     f32x4 a;
; #pragma unroll
;                     for (int e = 0; e < 4; ++e) { const float g = h[0][e]; a[e] = g * __builtin_amdgcn_rcpf(1.0f + __builtin_amdgcn_exp2f(-1.4426950408889634f * g)) * h[1][e]; }
;                     const unsigned p0 = cvt_pk_bf16(a[0], a[1]), p1 = cvt_pk_bf16(a[2], a[3]);
;                     if (n == 0) { pk_lo[ai][m][0] = p0; pk_lo[ai][m][1] = p1; }
;                     else { u32x4 w; w.x = pk_lo[ai][m][0]; w.y = pk_lo[ai][m][1]; w.z = p0; w.w = p1;
;                         *(u32x4*)(act + (size_t)(u.pm * BM + ai * HALF + wr * 64 + m * 16 + fr) * FF + gcol) = w; }
	v_fmac_f32_dpp v220, v188, v128 row_ror:2 row_mask:0xf bank_mask:0xf
	v_fmac_f32_dpp v221, v189, v129 row_ror:2 row_mask:0xf bank_mask:0xf
	v_fmac_f32_dpp v222, v196, v130 row_ror:2 row_mask:0xf bank_mask:0xf
	v_fmac_f32_dpp v223, v197, v131 row_ror:2 row_mask:0xf bank_mask:0xf
	v_fmac_f32_dpp v224, v200, v144 row_ror:2 row_mask:0xf bank_mask:0xf
	v_fmac_f32_dpp v225, v201, v145 row_ror:2 row_mask:0xf bank_mask:0xf
	v_fmac_f32_dpp v226, v204, v146 row_ror:2 row_mask:0xf bank_mask:0xf
	v_fmac_f32_dpp v227, v205, v147 row_ror:2 row_mask:0xf bank_mask:0xf
	v_pk_mul_f32 v[190:191], v[220:221], s[100:101] op_sel_hi:[1,0]
	v_pk_mul_f32 v[250:251], v[222:223], s[100:101] op_sel_hi:[1,0]
	v_exp_f32_e32 v190, v190
	v_exp_f32_e32 v191, v191
	v_exp_f32_e32 v250, v250
	v_exp_f32_e32 v251, v251
	v_pk_mul_f32 v[220:221], v[220:221], v[224:225]
	v_pk_mul_f32 v[222:223], v[222:223], v[226:227]
	v_pk_add_f32 v[190:191], v[190:191], 1.0 op_sel_hi:[1,0]
	v_pk_add_f32 v[250:251], v[250:251], 1.0 op_sel_hi:[1,0]
	v_rcp_f32_e32 v190, v190
	v_rcp_f32_e32 v191, v191
	v_rcp_f32_e32 v250, v250
	v_rcp_f32_e32 v251, v251
	v_pk_mul_f32 v[220:221], v[220:221], v[190:191]
	v_pk_mul_f32 v[222:223], v[222:223], v[250:251]
	v_cvt_pk_bf16_f32 v194, v220, v221
	v_cvt_pk_bf16_f32 v195, v222, v223
	v_pk_mul_f32 v[108:109], v[108:109], v[232:233] op_sel_hi:[1,0]
	v_pk_mul_f32 v[110:111], v[110:111], v[232:233] op_sel_hi:[1,0]
	v_pk_mul_f32 v[104:105], v[104:105], v[232:233] op_sel_hi:[1,0]
	v_pk_mul_f32 v[106:107], v[106:107], v[232:233] op_sel_hi:[1,0]
	v_pk_fma_f32 v[220:221], v[136:137], v[108:109], v[140:141]
	v_pk_fma_f32 v[222:223], v[138:139], v[110:111], v[142:143]
	v_pk_fma_f32 v[224:225], v[152:153], v[104:105], v[156:157]
	v_pk_fma_f32 v[226:227], v[154:155], v[106:107], v[158:159]
	v_cndmask_b32_e64 v188, v108, v116, s[98:99]
	v_cndmask_b32_e64 v189, v109, v117, s[98:99]
	v_cndmask_b32_e64 v196, v110, v118, s[98:99]
	v_cndmask_b32_e64 v197, v111, v119, s[98:99]
	v_cndmask_b32_e64 v200, v104, v112, s[98:99]
	v_cndmask_b32_e64 v201, v105, v113, s[98:99]
	v_cndmask_b32_e64 v204, v106, v114, s[98:99]
	v_cndmask_b32_e64 v205, v107, v115, s[98:99]
	v_fmac_f32_dpp v220, v188, v132 row_ror:1 row_mask:0xf bank_mask:0xf
	v_fmac_f32_dpp v221, v189, v133 row_ror:1 row_mask:0xf bank_mask:0xf
	v_fmac_f32_dpp v222, v196, v134 row_ror:1 row_mask:0xf bank_mask:0xf
	v_fmac_f32_dpp v223, v197, v135 row_ror:1 row_mask:0xf bank_mask:0xf
	v_fmac_f32_dpp v224, v200, v148 row_ror:1 row_mask:0xf bank_mask:0xf
	v_fmac_f32_dpp v225, v201, v149 row_ror:1 row_mask:0xf bank_mask:0xf
	v_fmac_f32_dpp v226, v204, v150 row_ror:1 row_mask:0xf bank_mask:0xf
	v_fmac_f32_dpp v227, v205, v151 row_ror:1 row_mask:0xf bank_mask:0xf
	v_cndmask_b32_e64 v188, v116, v108, s[40:41]
	v_cndmask_b32_e64 v189, v117, v109, s[40:41]
	v_cndmask_b32_e64 v196, v118, v110, s[40:41]
	v_cndmask_b32_e64 v197, v119, v111, s[40:41]
	v_cndmask_b32_e64 v200, v112, v104, s[40:41]
	v_cndmask_b32_e64 v201, v113, v105, s[40:41]
	v_cndmask_b32_e64 v204, v114, v106, s[40:41]
	v_cndmask_b32_e64 v205, v115, v107, s[40:41]
	v_fmac_f32_dpp v220, v188, v128 row_ror:2 row_mask:0xf bank_mask:0xf
	v_fmac_f32_dpp v221, v189, v129 row_ror:2 row_mask:0xf bank_mask:0xf
	v_fmac_f32_dpp v222, v196, v130 row_ror:2 row_mask:0xf bank_mask:0xf
	v_fmac_f32_dpp v223, v197, v131 row_ror:2 row_mask:0xf bank_mask:0xf
	v_fmac_f32_dpp v224, v200, v144 row_ror:2 row_mask:0xf bank_mask:0xf
	v_fmac_f32_dpp v225, v201, v145 row_ror:2 row_mask:0xf bank_mask:0xf
	v_fmac_f32_dpp v226, v204, v146 row_ror:2 row_mask:0xf bank_mask:0xf
	v_fmac_f32_dpp v227, v205, v147 row_ror:2 row_mask:0xf bank_mask:0xf
	v_pk_mul_f32 v[190:191], v[220:221], s[100:101] op_sel_hi:[1,0]
	v_pk_mul_f32 v[250:251], v[222:223], s[100:101] op_sel_hi:[1,0]
	v_exp_f32_e32 v190, v190
	v_exp_f32_e32 v191, v191
	v_exp_f32_e32 v250, v250
	v_exp_f32_e32 v251, v251
	v_pk_mul_f32 v[220:221], v[220:221], v[224:225]
	v_pk_mul_f32 v[222:223], v[222:223], v[226:227]
	v_pk_add_f32 v[190:191], v[190:191], 1.0 op_sel_hi:[1,0]
	v_pk_add_f32 v[250:251], v[250:251], 1.0 op_sel_hi:[1,0]
	v_rcp_f32_e32 v190, v190
	v_rcp_f32_e32 v191, v191
	v_rcp_f32_e32 v250, v250
	v_rcp_f32_e32 v251, v251
	v_pk_mul_f32 v[220:221], v[220:221], v[190:191]
	v_pk_mul_f32 v[222:223], v[222:223], v[250:251]
	v_cvt_pk_bf16_f32 v198, v220, v221
	v_cvt_pk_bf16_f32 v199, v222, v223
	v_pk_fma_f32 v[220:221], v[136:137], v[100:101], v[140:141]
	v_pk_fma_f32 v[222:223], v[138:139], v[102:103], v[142:143]
	v_pk_fma_f32 v[224:225], v[152:153], v[96:97], v[156:157]
	v_pk_fma_f32 v[226:227], v[154:155], v[98:99], v[158:159]
	v_cndmask_b32_e64 v188, v100, v108, s[98:99]
	v_cndmask_b32_e64 v189, v101, v109, s[98:99]
	v_cndmask_b32_e64 v196, v102, v110, s[98:99]
	v_cndmask_b32_e64 v197, v103, v111, s[98:99]
	v_cndmask_b32_e64 v200, v96, v104, s[98:99]
	v_cndmask_b32_e64 v201, v97, v105, s[98:99]
	v_cndmask_b32_e64 v204, v98, v106, s[98:99]
	v_cndmask_b32_e64 v205, v99, v107, s[98:99]
	v_fmac_f32_dpp v220, v188, v132 row_ror:1 row_mask:0xf bank_mask:0xf
	v_fmac_f32_dpp v221, v189, v133 row_ror:1 row_mask:0xf bank_mask:0xf
	v_fmac_f32_dpp v222, v196, v134 row_ror:1 row_mask:0xf bank_mask:0xf
	v_fmac_f32_dpp v223, v197, v135 row_ror:1 row_mask:0xf bank_mask:0xf
	v_fmac_f32_dpp v224, v200, v148 row_ror:1 row_mask:0xf bank_mask:0xf
	v_fmac_f32_dpp v225, v201, v149 row_ror:1 row_mask:0xf bank_mask:0xf
	v_fmac_f32_dpp v226, v204, v150 row_ror:1 row_mask:0xf bank_mask:0xf
	v_fmac_f32_dpp v227, v205, v151 row_ror:1 row_mask:0xf bank_mask:0xf
	v_cndmask_b32_e64 v188, v108, v100, s[40:41]
	v_cndmask_b32_e64 v189, v109, v101, s[40:41]
; __device__ __forceinline__ unsigned cvt_pk_bf16(float lo, float hi) { unsigned r; asm volatile("v_cvt_pk_bf16_f32 %0, %1, %2" : "=v"(r) : "v"(lo), "v"(hi)); return r; }
; __device__ __forceinline__ float dpp_ror1(float x) { return __int_as_float(__builtin_amdgcn_update_dpp(0, __float_as_int(x), 0x121, 0xf, 0xf, false)); }
; __device__ __forceinline__ float dpp_ror2(float x) { return __int_as_float(__builtin_amdgcn_update_dpp(0, __float_as_int(x), 0x122, 0xf, 0xf, false)); }
;     __device__ __forceinline__ void operator()(const f32x4 (&acc)[2][2][4][2], const Unit& u, int wr, int wc, int fr, int fq) const {
;     ...
;                 for (int bj = 0; bj < 2; ++bj) { const int col = bj * FF + gcol + 4;
;                     w0[bj] = *(const f32x4*)(cw + col); w1[bj] = *(const f32x4*)(cw + FF2 + col); w2[bj] = *(const f32x4*)(cw + 2 * FF2 + col); bb[bj] = *(const f32x4*)(cb + col); } }
;     ...
;                 for (int m = 0; m < 4; ++m) {
;                     f32x4 cur[2], h[2];
; #pragma unroll
;                     for (int bj = 0; bj < 2; ++bj) { cur[bj] = acc[ai][bj][m][n] * rs[ai][m]; f32x4 x1, x2;
; #pragma unroll
;                         for (int e = 0; e < 4; ++e) { const float c1 = dpp_ror1(cur[bj][e]), p1 = dpp_ror1(pg[bj][e]), c2 = dpp_ror2(cur[bj][e]), p2 = dpp_ror2(pg[bj][e]);
;                             x1[e] = fr >= 1 ? c1 : p1; x2[e] = fr >= 2 ? c2 : p2; }
;                         h[bj] = bb[bj] + w0[bj] * x2 + w1[bj] * x1 + w2[bj] * cur[bj]; }
;                     if (ai == 0 && wr == 0 && m == 0 && fr < 2) {
;                         *(f32x4*)(hc0 + (size_t)(u.pm * 2 + fr) * FF2 + gcol + 4 * n) = h[0]; *(f32x4*)(hc0 + (size_t)(u.pm * 2 + fr) * FF2 + FF + gcol + 4 * n) = h[1]; }
;                     f32x4 a;
; #pragma unroll
;                     for (int e = 0; e < 4; ++e) { const float g = h[0][e]; a[e] = g * __builtin_amdgcn_rcpf(1.0f + __builtin_amdgcn_exp2f(-1.4426950408889634f * g)) * h[1][e]; }
;                     const unsigned p0 = cvt_pk_bf16(a[0], a[1]), p1 = cvt_pk_bf16(a[2], a[3]);
;                     if (n == 0) { pk_lo[ai][m][0] = p0; pk_lo[ai][m][1] = p1; }
;                     else { u32x4 w; w.x = pk_lo[ai][m][0]; w.y = pk_lo[ai][m][1]; w.z = p0; w.w = p1;
;                         *(u32x4*)(act + (size_t)(u.pm * BM + ai * HALF + wr * 64 + m * 16 + fr) * FF + gcol) = w; }
	v_cndmask_b32_e64 v196, v110, v102, s[40:41]
	v_cndmask_b32_e64 v197, v111, v103, s[40:41]
	v_cndmask_b32_e64 v200, v104, v96, s[40:41]
	v_cndmask_b32_e64 v201, v105, v97, s[40:41]
	v_cndmask_b32_e64 v204, v106, v98, s[40:41]
	v_cndmask_b32_e64 v205, v107, v99, s[40:41]
	v_fmac_f32_dpp v220, v188, v128 row_ror:2 row_mask:0xf bank_mask:0xf
	v_fmac_f32_dpp v221, v189, v129 row_ror:2 row_mask:0xf bank_mask:0xf
	v_fmac_f32_dpp v222, v196, v130 row_ror:2 row_mask:0xf bank_mask:0xf
	v_fmac_f32_dpp v223, v197, v131 row_ror:2 row_mask:0xf bank_mask:0xf
	v_fmac_f32_dpp v224, v200, v144 row_ror:2 row_mask:0xf bank_mask:0xf
	v_fmac_f32_dpp v225, v201, v145 row_ror:2 row_mask:0xf bank_mask:0xf
	v_fmac_f32_dpp v226, v204, v146 row_ror:2 row_mask:0xf bank_mask:0xf
	v_fmac_f32_dpp v227, v205, v147 row_ror:2 row_mask:0xf bank_mask:0xf
	v_pk_mul_f32 v[190:191], v[220:221], s[100:101] op_sel_hi:[1,0]
	v_pk_mul_f32 v[250:251], v[222:223], s[100:101] op_sel_hi:[1,0]
	v_exp_f32_e32 v190, v190
	v_exp_f32_e32 v191, v191
	v_exp_f32_e32 v250, v250
	v_exp_f32_e32 v251, v251
	v_pk_mul_f32 v[220:221], v[220:221], v[224:225]
	v_pk_mul_f32 v[222:223], v[222:223], v[226:227]
	v_pk_add_f32 v[190:191], v[190:191], 1.0 op_sel_hi:[1,0]
	v_pk_add_f32 v[250:251], v[250:251], 1.0 op_sel_hi:[1,0]
	v_rcp_f32_e32 v190, v190
	v_rcp_f32_e32 v191, v191
	v_rcp_f32_e32 v250, v250
	v_rcp_f32_e32 v251, v251
	v_pk_mul_f32 v[220:221], v[220:221], v[190:191]
	v_pk_mul_f32 v[222:223], v[222:223], v[250:251]
	v_cvt_pk_bf16_f32 v202, v220, v221
	v_cvt_pk_bf16_f32 v203, v222, v223
	global_load_dwordx4 v[124:127], v233, s[14:15] offset:16
	global_load_dwordx4 v[116:119], v233, s[16:17] offset:16
	global_load_dwordx4 v[108:111], v233, s[92:93] offset:16
	global_load_dwordx4 v[100:103], v233, s[60:61] offset:16
	global_load_dwordx4 v[120:123], v235, s[14:15] offset:16
	global_load_dwordx4 v[112:115], v235, s[16:17] offset:16
	global_load_dwordx4 v[104:107], v235, s[92:93] offset:16
	global_load_dwordx4 v[96:99], v235, s[60:61] offset:16
	v_pk_mul_f32 v[92:93], v[92:93], v[236:237] op_sel_hi:[1,0]
	v_pk_mul_f32 v[94:95], v[94:95], v[236:237] op_sel_hi:[1,0]
	v_pk_mul_f32 v[88:89], v[88:89], v[236:237] op_sel_hi:[1,0]
	v_pk_mul_f32 v[90:91], v[90:91], v[236:237] op_sel_hi:[1,0]
	v_pk_fma_f32 v[220:221], v[136:137], v[92:93], v[140:141]
	v_pk_fma_f32 v[222:223], v[138:139], v[94:95], v[142:143]
	v_pk_fma_f32 v[224:225], v[152:153], v[88:89], v[156:157]
	v_pk_fma_f32 v[226:227], v[154:155], v[90:91], v[158:159]
	v_cndmask_b32_e64 v188, v92, v178, s[98:99]
	v_cndmask_b32_e64 v189, v93, v179, s[98:99]
	v_cndmask_b32_e64 v196, v94, v180, s[98:99]
	v_cndmask_b32_e64 v197, v95, v181, s[98:99]
	v_cndmask_b32_e64 v200, v88, v182, s[98:99]
	v_cndmask_b32_e64 v201, v89, v183, s[98:99]
	v_cndmask_b32_e64 v204, v90, v184, s[98:99]
	v_cndmask_b32_e64 v205, v91, v185, s[98:99]
	v_fmac_f32_dpp v220, v188, v132 row_ror:1 row_mask:0xf bank_mask:0xf
	v_fmac_f32_dpp v221, v189, v133 row_ror:1 row_mask:0xf bank_mask:0xf
	v_fmac_f32_dpp v222, v196, v134 row_ror:1 row_mask:0xf bank_mask:0xf
	v_fmac_f32_dpp v223, v197, v135 row_ror:1 row_mask:0xf bank_mask:0xf
	v_fmac_f32_dpp v224, v200, v148 row_ror:1 row_mask:0xf bank_mask:0xf
	v_fmac_f32_dpp v225, v201, v149 row_ror:1 row_mask:0xf bank_mask:0xf
	v_fmac_f32_dpp v226, v204, v150 row_ror:1 row_mask:0xf bank_mask:0xf
	v_fmac_f32_dpp v227, v205, v151 row_ror:1 row_mask:0xf bank_mask:0xf
	v_cndmask_b32_e64 v188, v178, v92, s[40:41]
	v_cndmask_b32_e64 v189, v179, v93, s[40:41]
	v_cndmask_b32_e64 v196, v180, v94, s[40:41]
	v_cndmask_b32_e64 v197, v181, v95, s[40:41]
	v_cndmask_b32_e64 v200, v182, v88, s[40:41]
	v_cndmask_b32_e64 v201, v183, v89, s[40:41]
	v_cndmask_b32_e64 v204, v184, v90, s[40:41]
	v_cndmask_b32_e64 v205, v185, v91, s[40:41]
	v_fmac_f32_dpp v220, v188, v128 row_ror:2 row_mask:0xf bank_mask:0xf
	v_fmac_f32_dpp v221, v189, v129 row_ror:2 row_mask:0xf bank_mask:0xf
	v_fmac_f32_dpp v222, v196, v130 row_ror:2 row_mask:0xf bank_mask:0xf
	v_fmac_f32_dpp v223, v197, v131 row_ror:2 row_mask:0xf bank_mask:0xf
	v_fmac_f32_dpp v224, v200, v144 row_ror:2 row_mask:0xf bank_mask:0xf
	v_fmac_f32_dpp v225, v201, v145 row_ror:2 row_mask:0xf bank_mask:0xf
	v_fmac_f32_dpp v226, v204, v146 row_ror:2 row_mask:0xf bank_mask:0xf
	v_fmac_f32_dpp v227, v205, v147 row_ror:2 row_mask:0xf bank_mask:0xf
	v_pk_mul_f32 v[190:191], v[220:221], s[100:101] op_sel_hi:[1,0]
	v_pk_mul_f32 v[250:251], v[222:223], s[100:101] op_sel_hi:[1,0]
	v_exp_f32_e32 v190, v190
	v_exp_f32_e32 v191, v191
	v_exp_f32_e32 v250, v250
	v_exp_f32_e32 v251, v251
	v_pk_mul_f32 v[220:221], v[220:221], v[224:225]
	v_pk_mul_f32 v[222:223], v[222:223], v[226:227]
	v_pk_add_f32 v[190:191], v[190:191], 1.0 op_sel_hi:[1,0]
	v_pk_add_f32 v[250:251], v[250:251], 1.0 op_sel_hi:[1,0]
	v_rcp_f32_e32 v190, v190
	v_rcp_f32_e32 v191, v191
	v_rcp_f32_e32 v250, v250
	v_rcp_f32_e32 v251, v251
	v_pk_mul_f32 v[220:221], v[220:221], v[190:191]
	v_pk_mul_f32 v[222:223], v[222:223], v[250:251]
	v_cvt_pk_bf16_f32 v160, v220, v221
	v_cvt_pk_bf16_f32 v161, v222, v223
	v_pk_mul_f32 v[84:85], v[84:85], v[238:239] op_sel_hi:[1,0]
	v_pk_mul_f32 v[86:87], v[86:87], v[238:239] op_sel_hi:[1,0]
	v_pk_mul_f32 v[80:81], v[80:81], v[238:239] op_sel_hi:[1,0]
	v_pk_mul_f32 v[82:83], v[82:83], v[238:239] op_sel_hi:[1,0]
	v_pk_fma_f32 v[220:221], v[136:137], v[84:85], v[140:141]
	v_pk_fma_f32 v[222:223], v[138:139], v[86:87], v[142:143]
	v_pk_fma_f32 v[224:225], v[152:153], v[80:81], v[156:157]
	v_pk_fma_f32 v[226:227], v[154:155], v[82:83], v[158:159]
	v_cndmask_b32_e64 v188, v84, v92, s[98:99]
	v_cndmask_b32_e64 v189, v85, v93, s[98:99]
; __device__ __forceinline__ unsigned cvt_pk_bf16(float lo, float hi) { unsigned r; asm volatile("v_cvt_pk_bf16_f32 %0, %1, %2" : "=v"(r) : "v"(lo), "v"(hi)); return r; }
; __device__ __forceinline__ float dpp_ror1(float x) { return __int_as_float(__builtin_amdgcn_update_dpp(0, __float_as_int(x), 0x121, 0xf, 0xf, false)); }
; __device__ __forceinline__ float dpp_ror2(float x) { return __int_as_float(__builtin_amdgcn_update_dpp(0, __float_as_int(x), 0x122, 0xf, 0xf, false)); }
;     __device__ __forceinline__ void operator()(const f32x4 (&acc)[2][2][4][2], const Unit& u, int wr, int wc, int fr, int fq) const {
;     ...
;                 for (int m = 0; m < 4; ++m) {
;                     f32x4 cur[2], h[2];
; #pragma unroll
;                     for (int bj = 0; bj < 2; ++bj) { cur[bj] = acc[ai][bj][m][n] * rs[ai][m]; f32x4 x1, x2;
; #pragma unroll
;                         for (int e = 0; e < 4; ++e) { const float c1 = dpp_ror1(cur[bj][e]), p1 = dpp_ror1(pg[bj][e]), c2 = dpp_ror2(cur[bj][e]), p2 = dpp_ror2(pg[bj][e]);
;                             x1[e] = fr >= 1 ? c1 : p1; x2[e] = fr >= 2 ? c2 : p2; }
;                         h[bj] = bb[bj] + w0[bj] * x2 + w1[bj] * x1 + w2[bj] * cur[bj]; }
;                     if (ai == 0 && wr == 0 && m == 0 && fr < 2) {
;                         *(f32x4*)(hc0 + (size_t)(u.pm * 2 + fr) * FF2 + gcol + 4 * n) = h[0]; *(f32x4*)(hc0 + (size_t)(u.pm * 2 + fr) * FF2 + FF + gcol + 4 * n) = h[1]; }
;                     f32x4 a;
; #pragma unroll
;                     for (int e = 0; e < 4; ++e) { const float g = h[0][e]; a[e] = g * __builtin_amdgcn_rcpf(1.0f + __builtin_amdgcn_exp2f(-1.4426950408889634f * g)) * h[1][e]; }
;                     const unsigned p0 = cvt_pk_bf16(a[0], a[1]), p1 = cvt_pk_bf16(a[2], a[3]);
;                     if (n == 0) { pk_lo[ai][m][0] = p0; pk_lo[ai][m][1] = p1; }
;                     else { u32x4 w; w.x = pk_lo[ai][m][0]; w.y = pk_lo[ai][m][1]; w.z = p0; w.w = p1;
;                         *(u32x4*)(act + (size_t)(u.pm * BM + ai * HALF + wr * 64 + m * 16 + fr) * FF + gcol) = w; }
	v_cndmask_b32_e64 v196, v86, v94, s[98:99]
	v_cndmask_b32_e64 v197, v87, v95, s[98:99]
	v_cndmask_b32_e64 v200, v80, v88, s[98:99]
	v_cndmask_b32_e64 v201, v81, v89, s[98:99]
	v_cndmask_b32_e64 v204, v82, v90, s[98:99]
	v_cndmask_b32_e64 v205, v83, v91, s[98:99]
	v_fmac_f32_dpp v220, v188, v132 row_ror:1 row_mask:0xf bank_mask:0xf
	v_fmac_f32_dpp v221, v189, v133 row_ror:1 row_mask:0xf bank_mask:0xf
	v_fmac_f32_dpp v222, v196, v134 row_ror:1 row_mask:0xf bank_mask:0xf
	v_fmac_f32_dpp v223, v197, v135 row_ror:1 row_mask:0xf bank_mask:0xf
	v_fmac_f32_dpp v224, v200, v148 row_ror:1 row_mask:0xf bank_mask:0xf
	v_fmac_f32_dpp v225, v201, v149 row_ror:1 row_mask:0xf bank_mask:0xf
	v_fmac_f32_dpp v226, v204, v150 row_ror:1 row_mask:0xf bank_mask:0xf
	v_fmac_f32_dpp v227, v205, v151 row_ror:1 row_mask:0xf bank_mask:0xf
	v_cndmask_b32_e64 v188, v92, v84, s[40:41]
	v_cndmask_b32_e64 v189, v93, v85, s[40:41]
	v_cndmask_b32_e64 v196, v94, v86, s[40:41]
	v_cndmask_b32_e64 v197, v95, v87, s[40:41]
	v_cndmask_b32_e64 v200, v88, v80, s[40:41]
	v_cndmask_b32_e64 v201, v89, v81, s[40:41]
	v_cndmask_b32_e64 v204, v90, v82, s[40:41]
	v_cndmask_b32_e64 v205, v91, v83, s[40:41]
	v_fmac_f32_dpp v220, v188, v128 row_ror:2 row_mask:0xf bank_mask:0xf
	v_fmac_f32_dpp v221, v189, v129 row_ror:2 row_mask:0xf bank_mask:0xf
	v_fmac_f32_dpp v222, v196, v130 row_ror:2 row_mask:0xf bank_mask:0xf
	v_fmac_f32_dpp v223, v197, v131 row_ror:2 row_mask:0xf bank_mask:0xf
	v_fmac_f32_dpp v224, v200, v144 row_ror:2 row_mask:0xf bank_mask:0xf
	v_fmac_f32_dpp v225, v201, v145 row_ror:2 row_mask:0xf bank_mask:0xf
	v_fmac_f32_dpp v226, v204, v146 row_ror:2 row_mask:0xf bank_mask:0xf
	v_fmac_f32_dpp v227, v205, v147 row_ror:2 row_mask:0xf bank_mask:0xf
	v_pk_mul_f32 v[190:191], v[220:221], s[100:101] op_sel_hi:[1,0]
	v_pk_mul_f32 v[250:251], v[222:223], s[100:101] op_sel_hi:[1,0]
	v_exp_f32_e32 v190, v190
	v_exp_f32_e32 v191, v191
	v_exp_f32_e32 v250, v250
	v_exp_f32_e32 v251, v251
	v_pk_mul_f32 v[220:221], v[220:221], v[224:225]
	v_pk_mul_f32 v[222:223], v[222:223], v[226:227]
	v_pk_add_f32 v[190:191], v[190:191], 1.0 op_sel_hi:[1,0]
	v_pk_add_f32 v[250:251], v[250:251], 1.0 op_sel_hi:[1,0]
	v_rcp_f32_e32 v190, v190
	v_rcp_f32_e32 v191, v191
	v_rcp_f32_e32 v250, v250
	v_rcp_f32_e32 v251, v251
	v_pk_mul_f32 v[220:221], v[220:221], v[190:191]
	v_pk_mul_f32 v[222:223], v[222:223], v[250:251]
	v_cvt_pk_bf16_f32 v164, v220, v221
	v_cvt_pk_bf16_f32 v165, v222, v223
	v_pk_mul_f32 v[76:77], v[76:77], v[240:241] op_sel_hi:[1,0]
	v_pk_mul_f32 v[78:79], v[78:79], v[240:241] op_sel_hi:[1,0]
	v_pk_mul_f32 v[72:73], v[72:73], v[240:241] op_sel_hi:[1,0]
	v_pk_mul_f32 v[74:75], v[74:75], v[240:241] op_sel_hi:[1,0]
	v_pk_fma_f32 v[220:221], v[136:137], v[76:77], v[140:141]
	v_pk_fma_f32 v[222:223], v[138:139], v[78:79], v[142:143]
	v_pk_fma_f32 v[224:225], v[152:153], v[72:73], v[156:157]
	v_pk_fma_f32 v[226:227], v[154:155], v[74:75], v[158:159]
	v_cndmask_b32_e64 v188, v76, v84, s[98:99]
	v_cndmask_b32_e64 v189, v77, v85, s[98:99]
	v_cndmask_b32_e64 v196, v78, v86, s[98:99]
	v_cndmask_b32_e64 v197, v79, v87, s[98:99]
	v_cndmask_b32_e64 v200, v72, v80, s[98:99]
	v_cndmask_b32_e64 v201, v73, v81, s[98:99]
	v_cndmask_b32_e64 v204, v74, v82, s[98:99]
	v_cndmask_b32_e64 v205, v75, v83, s[98:99]
	v_fmac_f32_dpp v220, v188, v132 row_ror:1 row_mask:0xf bank_mask:0xf
	v_fmac_f32_dpp v221, v189, v133 row_ror:1 row_mask:0xf bank_mask:0xf
	v_fmac_f32_dpp v222, v196, v134 row_ror:1 row_mask:0xf bank_mask:0xf
	v_fmac_f32_dpp v223, v197, v135 row_ror:1 row_mask:0xf bank_mask:0xf
	v_fmac_f32_dpp v224, v200, v148 row_ror:1 row_mask:0xf bank_mask:0xf
	v_fmac_f32_dpp v225, v201, v149 row_ror:1 row_mask:0xf bank_mask:0xf
	v_fmac_f32_dpp v226, v204, v150 row_ror:1 row_mask:0xf bank_mask:0xf
	v_fmac_f32_dpp v227, v205, v151 row_ror:1 row_mask:0xf bank_mask:0xf
	v_cndmask_b32_e64 v188, v84, v76, s[40:41]
	v_cndmask_b32_e64 v189, v85, v77, s[40:41]
	v_cndmask_b32_e64 v196, v86, v78, s[40:41]
	v_cndmask_b32_e64 v197, v87, v79, s[40:41]
	v_cndmask_b32_e64 v200, v80, v72, s[40:41]
	v_cndmask_b32_e64 v201, v81, v73, s[40:41]
	v_cndmask_b32_e64 v204, v82, v74, s[40:41]
	v_cndmask_b32_e64 v205, v83, v75, s[40:41]
	v_fmac_f32_dpp v220, v188, v128 row_ror:2 row_mask:0xf bank_mask:0xf
	v_fmac_f32_dpp v221, v189, v129 row_ror:2 row_mask:0xf bank_mask:0xf
	v_fmac_f32_dpp v222, v196, v130 row_ror:2 row_mask:0xf bank_mask:0xf
	v_fmac_f32_dpp v223, v197, v131 row_ror:2 row_mask:0xf bank_mask:0xf
	v_fmac_f32_dpp v224, v200, v144 row_ror:2 row_mask:0xf bank_mask:0xf
	v_fmac_f32_dpp v225, v201, v145 row_ror:2 row_mask:0xf bank_mask:0xf
	v_fmac_f32_dpp v226, v204, v146 row_ror:2 row_mask:0xf bank_mask:0xf
	v_fmac_f32_dpp v227, v205, v147 row_ror:2 row_mask:0xf bank_mask:0xf
	v_pk_mul_f32 v[190:191], v[220:221], s[100:101] op_sel_hi:[1,0]
	v_pk_mul_f32 v[250:251], v[222:223], s[100:101] op_sel_hi:[1,0]
	v_exp_f32_e32 v190, v190
	v_exp_f32_e32 v191, v191
	v_exp_f32_e32 v250, v250
	v_exp_f32_e32 v251, v251
	v_pk_mul_f32 v[220:221], v[220:221], v[224:225]
	v_pk_mul_f32 v[222:223], v[222:223], v[226:227]
	v_pk_add_f32 v[190:191], v[190:191], 1.0 op_sel_hi:[1,0]
	v_pk_add_f32 v[250:251], v[250:251], 1.0 op_sel_hi:[1,0]
	v_rcp_f32_e32 v190, v190
	v_rcp_f32_e32 v191, v191
	v_rcp_f32_e32 v250, v250
	v_rcp_f32_e32 v251, v251
	v_pk_mul_f32 v[220:221], v[220:221], v[190:191]
	v_pk_mul_f32 v[222:223], v[222:223], v[250:251]
	v_cvt_pk_bf16_f32 v178, v220, v221
	v_cvt_pk_bf16_f32 v179, v222, v223
	s_and_b64 vcc, exec, s[94:95]
	s_cbranch_vccnz .Lp7_hz1
	ds_read_b128 v[92:95], v215
	ds_read_b128 v[88:91], v216
	s_branch .Lp7_hr1

; __device__ __forceinline__ unsigned cvt_pk_bf16(float lo, float hi) { unsigned r; asm volatile("v_cvt_pk_bf16_f32 %0, %1, %2" : "=v"(r) : "v"(lo), "v"(hi)); return r; }
; __device__ __forceinline__ float dpp_ror1(float x) { return __int_as_float(__builtin_amdgcn_update_dpp(0, __float_as_int(x), 0x121, 0xf, 0xf, false)); }
; __device__ __forceinline__ float dpp_ror2(float x) { return __int_as_float(__builtin_amdgcn_update_dpp(0, __float_as_int(x), 0x122, 0xf, 0xf, false)); }
;     __device__ __forceinline__ void operator()(const f32x4 (&acc)[2][2][4][2], const Unit& u, int wr, int wc, int fr, int fq) const {
;     ...
;                 for (int m = 0; m < 4; ++m) {
;                     f32x4 cur[2], h[2];
; #pragma unroll
;                     for (int bj = 0; bj < 2; ++bj) { cur[bj] = acc[ai][bj][m][n] * rs[ai][m]; f32x4 x1, x2;
; #pragma unroll
;                         for (int e = 0; e < 4; ++e) { const float c1 = dpp_ror1(cur[bj][e]), p1 = dpp_ror1(pg[bj][e]), c2 = dpp_ror2(cur[bj][e]), p2 = dpp_ror2(pg[bj][e]);
;                             x1[e] = fr >= 1 ? c1 : p1; x2[e] = fr >= 2 ? c2 : p2; }
;                         h[bj] = bb[bj] + w0[bj] * x2 + w1[bj] * x1 + w2[bj] * cur[bj]; }
;                     if (ai == 0 && wr == 0 && m == 0 && fr < 2) {
;                         *(f32x4*)(hc0 + (size_t)(u.pm * 2 + fr) * FF2 + gcol + 4 * n) = h[0]; *(f32x4*)(hc0 + (size_t)(u.pm * 2 + fr) * FF2 + FF + gcol + 4 * n) = h[1]; }
;                     f32x4 a;
; #pragma unroll
;                     for (int e = 0; e < 4; ++e) { const float g = h[0][e]; a[e] = g * __builtin_amdgcn_rcpf(1.0f + __builtin_amdgcn_exp2f(-1.4426950408889634f * g)) * h[1][e]; }
;                     const unsigned p0 = cvt_pk_bf16(a[0], a[1]), p1 = cvt_pk_bf16(a[2], a[3]);
;                     if (n == 0) { pk_lo[ai][m][0] = p0; pk_lo[ai][m][1] = p1; }
;                     else { u32x4 w; w.x = pk_lo[ai][m][0]; w.y = pk_lo[ai][m][1]; w.z = p0; w.w = p1;
;                         *(u32x4*)(act + (size_t)(u.pm * BM + ai * HALF + wr * 64 + m * 16 + fr) * FF + gcol) = w; }
.Lp7_hr1:
	ds_read_b128 v[84:87], v217
	ds_read_b128 v[80:83], v218
	v_pk_fma_f32 v[220:221], v[136:137], v[68:69], v[140:141]
	v_pk_fma_f32 v[222:223], v[138:139], v[70:71], v[142:143]
	v_pk_fma_f32 v[224:225], v[152:153], v[64:65], v[156:157]
	v_pk_fma_f32 v[226:227], v[154:155], v[66:67], v[158:159]
	v_cndmask_b32_e64 v188, v68, v76, s[98:99]
	v_cndmask_b32_e64 v189, v69, v77, s[98:99]
	v_cndmask_b32_e64 v196, v70, v78, s[98:99]
	v_cndmask_b32_e64 v197, v71, v79, s[98:99]
	v_cndmask_b32_e64 v200, v64, v72, s[98:99]
	v_cndmask_b32_e64 v201, v65, v73, s[98:99]
	v_cndmask_b32_e64 v204, v66, v74, s[98:99]
	v_cndmask_b32_e64 v205, v67, v75, s[98:99]
	v_fmac_f32_dpp v220, v188, v132 row_ror:1 row_mask:0xf bank_mask:0xf
	v_fmac_f32_dpp v221, v189, v133 row_ror:1 row_mask:0xf bank_mask:0xf
	v_fmac_f32_dpp v222, v196, v134 row_ror:1 row_mask:0xf bank_mask:0xf
	v_fmac_f32_dpp v223, v197, v135 row_ror:1 row_mask:0xf bank_mask:0xf
	v_fmac_f32_dpp v224, v200, v148 row_ror:1 row_mask:0xf bank_mask:0xf
	v_fmac_f32_dpp v225, v201, v149 row_ror:1 row_mask:0xf bank_mask:0xf
	v_fmac_f32_dpp v226, v204, v150 row_ror:1 row_mask:0xf bank_mask:0xf
	v_fmac_f32_dpp v227, v205, v151 row_ror:1 row_mask:0xf bank_mask:0xf
	v_cndmask_b32_e64 v188, v76, v68, s[40:41]
	v_cndmask_b32_e64 v189, v77, v69, s[40:41]
	v_cndmask_b32_e64 v196, v78, v70, s[40:41]
	v_cndmask_b32_e64 v197, v79, v71, s[40:41]
	v_cndmask_b32_e64 v200, v72, v64, s[40:41]
	v_cndmask_b32_e64 v201, v73, v65, s[40:41]
	v_cndmask_b32_e64 v204, v74, v66, s[40:41]
	v_cndmask_b32_e64 v205, v75, v67, s[40:41]
	v_fmac_f32_dpp v220, v188, v128 row_ror:2 row_mask:0xf bank_mask:0xf
	v_fmac_f32_dpp v221, v189, v129 row_ror:2 row_mask:0xf bank_mask:0xf
	v_fmac_f32_dpp v222, v196, v130 row_ror:2 row_mask:0xf bank_mask:0xf
	v_fmac_f32_dpp v223, v197, v131 row_ror:2 row_mask:0xf bank_mask:0xf
	v_fmac_f32_dpp v224, v200, v144 row_ror:2 row_mask:0xf bank_mask:0xf
	v_fmac_f32_dpp v225, v201, v145 row_ror:2 row_mask:0xf bank_mask:0xf
	v_fmac_f32_dpp v226, v204, v146 row_ror:2 row_mask:0xf bank_mask:0xf
	v_fmac_f32_dpp v227, v205, v147 row_ror:2 row_mask:0xf bank_mask:0xf
	v_pk_mul_f32 v[190:191], v[220:221], s[100:101] op_sel_hi:[1,0]
	v_pk_mul_f32 v[250:251], v[222:223], s[100:101] op_sel_hi:[1,0]
	v_exp_f32_e32 v190, v190
	v_exp_f32_e32 v191, v191
	v_exp_f32_e32 v250, v250
	v_exp_f32_e32 v251, v251
	v_pk_mul_f32 v[220:221], v[220:221], v[224:225]
	v_pk_mul_f32 v[222:223], v[222:223], v[226:227]
	v_pk_add_f32 v[190:191], v[190:191], 1.0 op_sel_hi:[1,0]
	v_pk_add_f32 v[250:251], v[250:251], 1.0 op_sel_hi:[1,0]
	v_rcp_f32_e32 v190, v190
	v_rcp_f32_e32 v191, v191
	v_rcp_f32_e32 v250, v250
	v_rcp_f32_e32 v251, v251
	v_pk_mul_f32 v[220:221], v[220:221], v[190:191]
	v_pk_mul_f32 v[222:223], v[222:223], v[250:251]
	v_cvt_pk_bf16_f32 v182, v220, v221
	v_cvt_pk_bf16_f32 v183, v222, v223
	s_waitcnt vmcnt(0) lgkmcnt(0)
	v_pk_mul_f32 v[60:61], v[60:61], v[228:229] op_sel_hi:[1,0]
	v_pk_mul_f32 v[62:63], v[62:63], v[228:229] op_sel_hi:[1,0]
	v_pk_mul_f32 v[56:57], v[56:57], v[228:229] op_sel_hi:[1,0]
	v_pk_mul_f32 v[58:59], v[58:59], v[228:229] op_sel_hi:[1,0]
	v_pk_fma_f32 v[220:221], v[108:109], v[60:61], v[100:101]
	v_pk_fma_f32 v[222:223], v[110:111], v[62:63], v[102:103]
	v_pk_fma_f32 v[224:225], v[104:105], v[56:57], v[96:97]
	v_pk_fma_f32 v[226:227], v[106:107], v[58:59], v[98:99]
	v_cndmask_b32_e64 v72, v60, v92, s[98:99]
	v_cndmask_b32_e64 v73, v61, v93, s[98:99]
	v_cndmask_b32_e64 v74, v62, v94, s[98:99]
	v_cndmask_b32_e64 v75, v63, v95, s[98:99]
	v_cndmask_b32_e64 v76, v56, v88, s[98:99]
	v_cndmask_b32_e64 v77, v57, v89, s[98:99]
	v_cndmask_b32_e64 v78, v58, v90, s[98:99]
	v_cndmask_b32_e64 v79, v59, v91, s[98:99]
	v_fmac_f32_dpp v220, v72, v116 row_ror:1 row_mask:0xf bank_mask:0xf
	v_fmac_f32_dpp v221, v73, v117 row_ror:1 row_mask:0xf bank_mask:0xf
	v_fmac_f32_dpp v222, v74, v118 row_ror:1 row_mask:0xf bank_mask:0xf
	v_fmac_f32_dpp v223, v75, v119 row_ror:1 row_mask:0xf bank_mask:0xf
	v_fmac_f32_dpp v224, v76, v112 row_ror:1 row_mask:0xf bank_mask:0xf
	v_fmac_f32_dpp v225, v77, v113 row_ror:1 row_mask:0xf bank_mask:0xf
	v_fmac_f32_dpp v226, v78, v114 row_ror:1 row_mask:0xf bank_mask:0xf
	v_fmac_f32_dpp v227, v79, v115 row_ror:1 row_mask:0xf bank_mask:0xf
	v_cndmask_b32_e64 v72, v92, v60, s[40:41]
	v_cndmask_b32_e64 v73, v93, v61, s[40:41]
	v_cndmask_b32_e64 v74, v94, v62, s[40:41]
	v_cndmask_b32_e64 v75, v95, v63, s[40:41]
	v_cndmask_b32_e64 v76, v88, v56, s[40:41]
	v_cndmask_b32_e64 v77, v89, v57, s[40:41]
	v_cndmask_b32_e64 v78, v90, v58, s[40:41]
	v_cndmask_b32_e64 v79, v91, v59, s[40:41]
	v_fmac_f32_dpp v220, v72, v124 row_ror:2 row_mask:0xf bank_mask:0xf
	v_fmac_f32_dpp v221, v73, v125 row_ror:2 row_mask:0xf bank_mask:0xf
	v_fmac_f32_dpp v222, v74, v126 row_ror:2 row_mask:0xf bank_mask:0xf
	v_fmac_f32_dpp v223, v75, v127 row_ror:2 row_mask:0xf bank_mask:0xf
	v_fmac_f32_dpp v224, v76, v120 row_ror:2 row_mask:0xf bank_mask:0xf
	v_fmac_f32_dpp v225, v77, v121 row_ror:2 row_mask:0xf bank_mask:0xf
	v_fmac_f32_dpp v226, v78, v122 row_ror:2 row_mask:0xf bank_mask:0xf
	v_fmac_f32_dpp v227, v79, v123 row_ror:2 row_mask:0xf bank_mask:0xf
	s_and_saveexec_b64 s[0:1], s[12:13]
	global_store_dwordx4 v241, v[220:223], s[84:85] offset:16
	global_store_dwordx4 v249, v[224:227], s[84:85] offset:16
	s_or_b64 exec, exec, s[0:1]
	v_pk_mul_f32 v[190:191], v[220:221], s[100:101] op_sel_hi:[1,0]
	v_pk_mul_f32 v[250:251], v[222:223], s[100:101] op_sel_hi:[1,0]
	v_exp_f32_e32 v190, v190
	v_exp_f32_e32 v191, v191
	v_exp_f32_e32 v250, v250
	v_exp_f32_e32 v251, v251
	v_pk_mul_f32 v[220:221], v[220:221], v[224:225]
; __device__ __forceinline__ unsigned cvt_pk_bf16(float lo, float hi) { unsigned r; asm volatile("v_cvt_pk_bf16_f32 %0, %1, %2" : "=v"(r) : "v"(lo), "v"(hi)); return r; }
; __device__ __forceinline__ float dpp_ror1(float x) { return __int_as_float(__builtin_amdgcn_update_dpp(0, __float_as_int(x), 0x121, 0xf, 0xf, false)); }
; __device__ __forceinline__ float dpp_ror2(float x) { return __int_as_float(__builtin_amdgcn_update_dpp(0, __float_as_int(x), 0x122, 0xf, 0xf, false)); }
;     __device__ __forceinline__ void operator()(const f32x4 (&acc)[2][2][4][2], const Unit& u, int wr, int wc, int fr, int fq) const {
;     ...
;                 for (int m = 0; m < 4; ++m) {
;                     f32x4 cur[2], h[2];
; #pragma unroll
;                     for (int bj = 0; bj < 2; ++bj) { cur[bj] = acc[ai][bj][m][n] * rs[ai][m]; f32x4 x1, x2;
; #pragma unroll
;                         for (int e = 0; e < 4; ++e) { const float c1 = dpp_ror1(cur[bj][e]), p1 = dpp_ror1(pg[bj][e]), c2 = dpp_ror2(cur[bj][e]), p2 = dpp_ror2(pg[bj][e]);
;                             x1[e] = fr >= 1 ? c1 : p1; x2[e] = fr >= 2 ? c2 : p2; }
;                         h[bj] = bb[bj] + w0[bj] * x2 + w1[bj] * x1 + w2[bj] * cur[bj]; }
;                     if (ai == 0 && wr == 0 && m == 0 && fr < 2) {
;                         *(f32x4*)(hc0 + (size_t)(u.pm * 2 + fr) * FF2 + gcol + 4 * n) = h[0]; *(f32x4*)(hc0 + (size_t)(u.pm * 2 + fr) * FF2 + FF + gcol + 4 * n) = h[1]; }
;                     f32x4 a;
; #pragma unroll
;                     for (int e = 0; e < 4; ++e) { const float g = h[0][e]; a[e] = g * __builtin_amdgcn_rcpf(1.0f + __builtin_amdgcn_exp2f(-1.4426950408889634f * g)) * h[1][e]; }
;                     const unsigned p0 = cvt_pk_bf16(a[0], a[1]), p1 = cvt_pk_bf16(a[2], a[3]);
;                     if (n == 0) { pk_lo[ai][m][0] = p0; pk_lo[ai][m][1] = p1; }
;                     else { u32x4 w; w.x = pk_lo[ai][m][0]; w.y = pk_lo[ai][m][1]; w.z = p0; w.w = p1;
;                         *(u32x4*)(act + (size_t)(u.pm * BM + ai * HALF + wr * 64 + m * 16 + fr) * FF + gcol) = w; }
	v_pk_mul_f32 v[222:223], v[222:223], v[226:227]
	v_pk_add_f32 v[190:191], v[190:191], 1.0 op_sel_hi:[1,0]
	v_pk_add_f32 v[250:251], v[250:251], 1.0 op_sel_hi:[1,0]
	v_rcp_f32_e32 v190, v190
	v_rcp_f32_e32 v191, v191
	v_rcp_f32_e32 v250, v250
	v_rcp_f32_e32 v251, v251
	v_pk_mul_f32 v[220:221], v[220:221], v[190:191]
	v_pk_mul_f32 v[222:223], v[222:223], v[250:251]
	v_cvt_pk_bf16_f32 v188, v220, v221
	v_cvt_pk_bf16_f32 v189, v222, v223
	global_store_dwordx4 v239, v[186:189], s[24:25]
	v_pk_mul_f32 v[52:53], v[52:53], v[230:231] op_sel_hi:[1,0]
	v_pk_mul_f32 v[54:55], v[54:55], v[230:231] op_sel_hi:[1,0]
	v_pk_mul_f32 v[48:49], v[48:49], v[230:231] op_sel_hi:[1,0]
	v_pk_mul_f32 v[50:51], v[50:51], v[230:231] op_sel_hi:[1,0]
	v_pk_fma_f32 v[220:221], v[108:109], v[52:53], v[100:101]
	v_pk_fma_f32 v[222:223], v[110:111], v[54:55], v[102:103]
	v_pk_fma_f32 v[224:225], v[104:105], v[48:49], v[96:97]
	v_pk_fma_f32 v[226:227], v[106:107], v[50:51], v[98:99]
	v_cndmask_b32_e64 v72, v52, v60, s[98:99]
	v_cndmask_b32_e64 v73, v53, v61, s[98:99]
	v_cndmask_b32_e64 v74, v54, v62, s[98:99]
	v_cndmask_b32_e64 v75, v55, v63, s[98:99]
	v_cndmask_b32_e64 v76, v48, v56, s[98:99]
	v_cndmask_b32_e64 v77, v49, v57, s[98:99]
	v_cndmask_b32_e64 v78, v50, v58, s[98:99]
	v_cndmask_b32_e64 v79, v51, v59, s[98:99]
	v_fmac_f32_dpp v220, v72, v116 row_ror:1 row_mask:0xf bank_mask:0xf
	v_fmac_f32_dpp v221, v73, v117 row_ror:1 row_mask:0xf bank_mask:0xf
	v_fmac_f32_dpp v222, v74, v118 row_ror:1 row_mask:0xf bank_mask:0xf
	v_fmac_f32_dpp v223, v75, v119 row_ror:1 row_mask:0xf bank_mask:0xf
	v_fmac_f32_dpp v224, v76, v112 row_ror:1 row_mask:0xf bank_mask:0xf
	v_fmac_f32_dpp v225, v77, v113 row_ror:1 row_mask:0xf bank_mask:0xf
	v_fmac_f32_dpp v226, v78, v114 row_ror:1 row_mask:0xf bank_mask:0xf
	v_fmac_f32_dpp v227, v79, v115 row_ror:1 row_mask:0xf bank_mask:0xf
	v_cndmask_b32_e64 v72, v60, v52, s[40:41]
	v_cndmask_b32_e64 v73, v61, v53, s[40:41]
	v_cndmask_b32_e64 v74, v62, v54, s[40:41]
	v_cndmask_b32_e64 v75, v63, v55, s[40:41]
	v_cndmask_b32_e64 v76, v56, v48, s[40:41]
	v_cndmask_b32_e64 v77, v57, v49, s[40:41]
	v_cndmask_b32_e64 v78, v58, v50, s[40:41]
	v_cndmask_b32_e64 v79, v59, v51, s[40:41]
	v_fmac_f32_dpp v220, v72, v124 row_ror:2 row_mask:0xf bank_mask:0xf
	v_fmac_f32_dpp v221, v73, v125 row_ror:2 row_mask:0xf bank_mask:0xf
	v_fmac_f32_dpp v222, v74, v126 row_ror:2 row_mask:0xf bank_mask:0xf
	v_fmac_f32_dpp v223, v75, v127 row_ror:2 row_mask:0xf bank_mask:0xf
	v_fmac_f32_dpp v224, v76, v120 row_ror:2 row_mask:0xf bank_mask:0xf
	v_fmac_f32_dpp v225, v77, v121 row_ror:2 row_mask:0xf bank_mask:0xf
	v_fmac_f32_dpp v226, v78, v122 row_ror:2 row_mask:0xf bank_mask:0xf
	v_fmac_f32_dpp v227, v79, v123 row_ror:2 row_mask:0xf bank_mask:0xf
	v_pk_mul_f32 v[190:191], v[220:221], s[100:101] op_sel_hi:[1,0]
	v_pk_mul_f32 v[250:251], v[222:223], s[100:101] op_sel_hi:[1,0]
	v_exp_f32_e32 v190, v190
	v_exp_f32_e32 v191, v191
	v_exp_f32_e32 v250, v250
	v_exp_f32_e32 v251, v251
	v_pk_mul_f32 v[220:221], v[220:221], v[224:225]
	v_pk_mul_f32 v[222:223], v[222:223], v[226:227]
	v_pk_add_f32 v[190:191], v[190:191], 1.0 op_sel_hi:[1,0]
	v_pk_add_f32 v[250:251], v[250:251], 1.0 op_sel_hi:[1,0]
	v_rcp_f32_e32 v190, v190
	v_rcp_f32_e32 v191, v191
	v_rcp_f32_e32 v250, v250
	v_rcp_f32_e32 v251, v251
	v_pk_mul_f32 v[220:221], v[220:221], v[190:191]
	v_pk_mul_f32 v[222:223], v[222:223], v[250:251]
	v_cvt_pk_bf16_f32 v196, v220, v221
	v_cvt_pk_bf16_f32 v197, v222, v223
	v_add_u32_e32 v243, 0x16000, v239
	global_store_dwordx4 v243, v[194:197], s[24:25]
	v_pk_mul_f32 v[44:45], v[44:45], v[232:233] op_sel_hi:[1,0]
	v_pk_mul_f32 v[46:47], v[46:47], v[232:233] op_sel_hi:[1,0]
	v_pk_mul_f32 v[40:41], v[40:41], v[232:233] op_sel_hi:[1,0]
	v_pk_mul_f32 v[42:43], v[42:43], v[232:233] op_sel_hi:[1,0]
	v_pk_fma_f32 v[220:221], v[108:109], v[44:45], v[100:101]
	v_pk_fma_f32 v[222:223], v[110:111], v[46:47], v[102:103]
	v_pk_fma_f32 v[224:225], v[104:105], v[40:41], v[96:97]
	v_pk_fma_f32 v[226:227], v[106:107], v[42:43], v[98:99]
	v_cndmask_b32_e64 v72, v44, v52, s[98:99]
	v_cndmask_b32_e64 v73, v45, v53, s[98:99]
	v_cndmask_b32_e64 v74, v46, v54, s[98:99]
	v_cndmask_b32_e64 v75, v47, v55, s[98:99]
	v_cndmask_b32_e64 v76, v40, v48, s[98:99]
	v_cndmask_b32_e64 v77, v41, v49, s[98:99]
	v_cndmask_b32_e64 v78, v42, v50, s[98:99]
	v_cndmask_b32_e64 v79, v43, v51, s[98:99]
	v_fmac_f32_dpp v220, v72, v116 row_ror:1 row_mask:0xf bank_mask:0xf
	v_fmac_f32_dpp v221, v73, v117 row_ror:1 row_mask:0xf bank_mask:0xf
	v_fmac_f32_dpp v222, v74, v118 row_ror:1 row_mask:0xf bank_mask:0xf
	v_fmac_f32_dpp v223, v75, v119 row_ror:1 row_mask:0xf bank_mask:0xf
	v_fmac_f32_dpp v224, v76, v112 row_ror:1 row_mask:0xf bank_mask:0xf
	v_fmac_f32_dpp v225, v77, v113 row_ror:1 row_mask:0xf bank_mask:0xf
	v_fmac_f32_dpp v226, v78, v114 row_ror:1 row_mask:0xf bank_mask:0xf
	v_fmac_f32_dpp v227, v79, v115 row_ror:1 row_mask:0xf bank_mask:0xf
	v_cndmask_b32_e64 v72, v52, v44, s[40:41]
	v_cndmask_b32_e64 v73, v53, v45, s[40:41]
	v_cndmask_b32_e64 v74, v54, v46, s[40:41]
	v_cndmask_b32_e64 v75, v55, v47, s[40:41]
	v_cndmask_b32_e64 v76, v48, v40, s[40:41]
	v_cndmask_b32_e64 v77, v49, v41, s[40:41]
	v_cndmask_b32_e64 v78, v50, v42, s[40:41]
	v_cndmask_b32_e64 v79, v51, v43, s[40:41]
	v_fmac_f32_dpp v220, v72, v124 row_ror:2 row_mask:0xf bank_mask:0xf
	v_fmac_f32_dpp v221, v73, v125 row_ror:2 row_mask:0xf bank_mask:0xf
	v_fmac_f32_dpp v222, v74, v126 row_ror:2 row_mask:0xf bank_mask:0xf
	v_fmac_f32_dpp v223, v75, v127 row_ror:2 row_mask:0xf bank_mask:0xf
	v_fmac_f32_dpp v224, v76, v120 row_ror:2 row_mask:0xf bank_mask:0xf
; __device__ __forceinline__ unsigned cvt_pk_bf16(float lo, float hi) { unsigned r; asm volatile("v_cvt_pk_bf16_f32 %0, %1, %2" : "=v"(r) : "v"(lo), "v"(hi)); return r; }
; __device__ __forceinline__ float dpp_ror1(float x) { return __int_as_float(__builtin_amdgcn_update_dpp(0, __float_as_int(x), 0x121, 0xf, 0xf, false)); }
; __device__ __forceinline__ float dpp_ror2(float x) { return __int_as_float(__builtin_amdgcn_update_dpp(0, __float_as_int(x), 0x122, 0xf, 0xf, false)); }
; __device__ __forceinline__ float row_rstd(const float* slots, int row) {
;     const f32x4* s = (const f32x4*)(slots + (size_t)row * 16);
;     const f32x4 a = s[0], b = s[1], c = s[2], d = s[3];
;     __device__ __forceinline__ void operator()(const f32x4 (&acc)[2][2][4][2], const Unit& u, int wr, int wc, int fr, int fq) const {
;     ...
;                 for (int m = 0; m < 4; ++m) {
;                     f32x4 cur[2], h[2];
; #pragma unroll
;                     for (int bj = 0; bj < 2; ++bj) { cur[bj] = acc[ai][bj][m][n] * rs[ai][m]; f32x4 x1, x2;
; #pragma unroll
;                         for (int e = 0; e < 4; ++e) { const float c1 = dpp_ror1(cur[bj][e]), p1 = dpp_ror1(pg[bj][e]), c2 = dpp_ror2(cur[bj][e]), p2 = dpp_ror2(pg[bj][e]);
;                             x1[e] = fr >= 1 ? c1 : p1; x2[e] = fr >= 2 ? c2 : p2; }
;                         h[bj] = bb[bj] + w0[bj] * x2 + w1[bj] * x1 + w2[bj] * cur[bj]; }
;                     if (ai == 0 && wr == 0 && m == 0 && fr < 2) {
;                         *(f32x4*)(hc0 + (size_t)(u.pm * 2 + fr) * FF2 + gcol + 4 * n) = h[0]; *(f32x4*)(hc0 + (size_t)(u.pm * 2 + fr) * FF2 + FF + gcol + 4 * n) = h[1]; }
;                     f32x4 a;
; #pragma unroll
;                     for (int e = 0; e < 4; ++e) { const float g = h[0][e]; a[e] = g * __builtin_amdgcn_rcpf(1.0f + __builtin_amdgcn_exp2f(-1.4426950408889634f * g)) * h[1][e]; }
;                     const unsigned p0 = cvt_pk_bf16(a[0], a[1]), p1 = cvt_pk_bf16(a[2], a[3]);
;                     if (n == 0) { pk_lo[ai][m][0] = p0; pk_lo[ai][m][1] = p1; }
;                     else { u32x4 w; w.x = pk_lo[ai][m][0]; w.y = pk_lo[ai][m][1]; w.z = p0; w.w = p1;
;                         *(u32x4*)(act + (size_t)(u.pm * BM + ai * HALF + wr * 64 + m * 16 + fr) * FF + gcol) = w; }
	v_fmac_f32_dpp v225, v77, v121 row_ror:2 row_mask:0xf bank_mask:0xf
	v_fmac_f32_dpp v226, v78, v122 row_ror:2 row_mask:0xf bank_mask:0xf
	v_fmac_f32_dpp v227, v79, v123 row_ror:2 row_mask:0xf bank_mask:0xf
	v_pk_mul_f32 v[190:191], v[220:221], s[100:101] op_sel_hi:[1,0]
	v_pk_mul_f32 v[250:251], v[222:223], s[100:101] op_sel_hi:[1,0]
	v_exp_f32_e32 v190, v190
	v_exp_f32_e32 v191, v191
	v_exp_f32_e32 v250, v250
	v_exp_f32_e32 v251, v251
	v_pk_mul_f32 v[220:221], v[220:221], v[224:225]
	v_pk_mul_f32 v[222:223], v[222:223], v[226:227]
	v_pk_add_f32 v[190:191], v[190:191], 1.0 op_sel_hi:[1,0]
	v_pk_add_f32 v[250:251], v[250:251], 1.0 op_sel_hi:[1,0]
	v_rcp_f32_e32 v190, v190
	v_rcp_f32_e32 v191, v191
	v_rcp_f32_e32 v250, v250
	v_rcp_f32_e32 v251, v251
	v_pk_mul_f32 v[220:221], v[220:221], v[190:191]
	v_pk_mul_f32 v[222:223], v[222:223], v[250:251]
	v_cvt_pk_bf16_f32 v200, v220, v221
	v_cvt_pk_bf16_f32 v201, v222, v223
	v_add_u32_e32 v243, 0x2c000, v239
	global_store_dwordx4 v243, v[198:201], s[24:25]
	v_pk_fma_f32 v[220:221], v[108:109], v[36:37], v[100:101]
	v_pk_fma_f32 v[222:223], v[110:111], v[38:39], v[102:103]
	v_pk_fma_f32 v[224:225], v[104:105], v[32:33], v[96:97]
	v_pk_fma_f32 v[226:227], v[106:107], v[34:35], v[98:99]
	v_cndmask_b32_e64 v72, v36, v44, s[98:99]
	v_cndmask_b32_e64 v73, v37, v45, s[98:99]
	v_cndmask_b32_e64 v74, v38, v46, s[98:99]
	v_cndmask_b32_e64 v75, v39, v47, s[98:99]
	v_cndmask_b32_e64 v76, v32, v40, s[98:99]
	v_cndmask_b32_e64 v77, v33, v41, s[98:99]
	v_cndmask_b32_e64 v78, v34, v42, s[98:99]
	v_cndmask_b32_e64 v79, v35, v43, s[98:99]
	v_fmac_f32_dpp v220, v72, v116 row_ror:1 row_mask:0xf bank_mask:0xf
	v_fmac_f32_dpp v221, v73, v117 row_ror:1 row_mask:0xf bank_mask:0xf
	v_fmac_f32_dpp v222, v74, v118 row_ror:1 row_mask:0xf bank_mask:0xf
	v_fmac_f32_dpp v223, v75, v119 row_ror:1 row_mask:0xf bank_mask:0xf
	v_fmac_f32_dpp v224, v76, v112 row_ror:1 row_mask:0xf bank_mask:0xf
	v_fmac_f32_dpp v225, v77, v113 row_ror:1 row_mask:0xf bank_mask:0xf
	v_fmac_f32_dpp v226, v78, v114 row_ror:1 row_mask:0xf bank_mask:0xf
	v_fmac_f32_dpp v227, v79, v115 row_ror:1 row_mask:0xf bank_mask:0xf
	v_cndmask_b32_e64 v72, v44, v36, s[40:41]
	v_cndmask_b32_e64 v73, v45, v37, s[40:41]
	v_cndmask_b32_e64 v74, v46, v38, s[40:41]
	v_cndmask_b32_e64 v75, v47, v39, s[40:41]
	v_cndmask_b32_e64 v76, v40, v32, s[40:41]
	v_cndmask_b32_e64 v77, v41, v33, s[40:41]
	v_cndmask_b32_e64 v78, v42, v34, s[40:41]
	v_cndmask_b32_e64 v79, v43, v35, s[40:41]
	v_fmac_f32_dpp v220, v72, v124 row_ror:2 row_mask:0xf bank_mask:0xf
	v_fmac_f32_dpp v221, v73, v125 row_ror:2 row_mask:0xf bank_mask:0xf
	v_fmac_f32_dpp v222, v74, v126 row_ror:2 row_mask:0xf bank_mask:0xf
	v_fmac_f32_dpp v223, v75, v127 row_ror:2 row_mask:0xf bank_mask:0xf
	v_fmac_f32_dpp v224, v76, v120 row_ror:2 row_mask:0xf bank_mask:0xf
	v_fmac_f32_dpp v225, v77, v121 row_ror:2 row_mask:0xf bank_mask:0xf
	v_fmac_f32_dpp v226, v78, v122 row_ror:2 row_mask:0xf bank_mask:0xf
	v_fmac_f32_dpp v227, v79, v123 row_ror:2 row_mask:0xf bank_mask:0xf
	v_pk_mul_f32 v[190:191], v[220:221], s[100:101] op_sel_hi:[1,0]
	v_pk_mul_f32 v[250:251], v[222:223], s[100:101] op_sel_hi:[1,0]
	v_exp_f32_e32 v190, v190
	v_exp_f32_e32 v191, v191
	v_exp_f32_e32 v250, v250
	v_exp_f32_e32 v251, v251
	v_pk_mul_f32 v[220:221], v[220:221], v[224:225]
	v_pk_mul_f32 v[222:223], v[222:223], v[226:227]
	v_pk_add_f32 v[190:191], v[190:191], 1.0 op_sel_hi:[1,0]
	v_pk_add_f32 v[250:251], v[250:251], 1.0 op_sel_hi:[1,0]
	v_rcp_f32_e32 v190, v190
	v_rcp_f32_e32 v191, v191
	v_rcp_f32_e32 v250, v250
	v_rcp_f32_e32 v251, v251
	v_pk_mul_f32 v[220:221], v[220:221], v[190:191]
	v_pk_mul_f32 v[222:223], v[222:223], v[250:251]
	v_cvt_pk_bf16_f32 v204, v220, v221
	v_cvt_pk_bf16_f32 v205, v222, v223
	v_add_u32_e32 v243, 0x42000, v239
	global_store_dwordx4 v243, v[202:205], s[24:25]
	s_and_b64 vcc, exec, s[46:47]
	s_cbranch_vccz .Lp7_nopf
	s_cmp_eq_u32 s10, s71
	s_cbranch_scc1 .Lp7_nopf
	s_lshl_b32 s78, s10, 8
	s_add_i32 s78, s78, s8
	s_mov_b32 s79, 1
	v_or_b32_e32 v229, s78, v209
	v_lshlrev_b32_e32 v229, 6, v229
	v_add_u32_e32 v231, 0x2000, v229
	global_load_dwordx4 v[60:63], v229, s[26:27]
	global_load_dwordx4 v[52:55], v229, s[26:27] offset:16
	global_load_dwordx4 v[44:47], v229, s[26:27] offset:32
	global_load_dwordx4 v[36:39], v229, s[26:27] offset:48
	global_load_dwordx4 v[56:59], v231, s[26:27]
	global_load_dwordx4 v[48:51], v231, s[26:27] offset:16
	global_load_dwordx4 v[40:43], v231, s[26:27] offset:32
	global_load_dwordx4 v[32:35], v231, s[26:27] offset:48
; __device__ __forceinline__ unsigned cvt_pk_bf16(float lo, float hi) { unsigned r; asm volatile("v_cvt_pk_bf16_f32 %0, %1, %2" : "=v"(r) : "v"(lo), "v"(hi)); return r; }
; __device__ __forceinline__ float dpp_ror1(float x) { return __int_as_float(__builtin_amdgcn_update_dpp(0, __float_as_int(x), 0x121, 0xf, 0xf, false)); }
; __device__ __forceinline__ float dpp_ror2(float x) { return __int_as_float(__builtin_amdgcn_update_dpp(0, __float_as_int(x), 0x122, 0xf, 0xf, false)); }
;     __device__ __forceinline__ void operator()(const f32x4 (&acc)[2][2][4][2], const Unit& u, int wr, int wc, int fr, int fq) const {
;     ...
;                 for (int m = 0; m < 4; ++m) {
;                     f32x4 cur[2], h[2];
; #pragma unroll
;                     for (int bj = 0; bj < 2; ++bj) { cur[bj] = acc[ai][bj][m][n] * rs[ai][m]; f32x4 x1, x2;
; #pragma unroll
;                         for (int e = 0; e < 4; ++e) { const float c1 = dpp_ror1(cur[bj][e]), p1 = dpp_ror1(pg[bj][e]), c2 = dpp_ror2(cur[bj][e]), p2 = dpp_ror2(pg[bj][e]);
;                             x1[e] = fr >= 1 ? c1 : p1; x2[e] = fr >= 2 ? c2 : p2; }
;                         h[bj] = bb[bj] + w0[bj] * x2 + w1[bj] * x1 + w2[bj] * cur[bj]; }
;                     if (ai == 0 && wr == 0 && m == 0 && fr < 2) {
;                         *(f32x4*)(hc0 + (size_t)(u.pm * 2 + fr) * FF2 + gcol + 4 * n) = h[0]; *(f32x4*)(hc0 + (size_t)(u.pm * 2 + fr) * FF2 + FF + gcol + 4 * n) = h[1]; }
;                     f32x4 a;
; #pragma unroll
;                     for (int e = 0; e < 4; ++e) { const float g = h[0][e]; a[e] = g * __builtin_amdgcn_rcpf(1.0f + __builtin_amdgcn_exp2f(-1.4426950408889634f * g)) * h[1][e]; }
;                     const unsigned p0 = cvt_pk_bf16(a[0], a[1]), p1 = cvt_pk_bf16(a[2], a[3]);
;                     if (n == 0) { pk_lo[ai][m][0] = p0; pk_lo[ai][m][1] = p1; }
;                     else { u32x4 w; w.x = pk_lo[ai][m][0]; w.y = pk_lo[ai][m][1]; w.z = p0; w.w = p1;
;                         *(u32x4*)(act + (size_t)(u.pm * BM + ai * HALF + wr * 64 + m * 16 + fr) * FF + gcol) = w; }
.Lp7_nopf:
	v_pk_mul_f32 v[28:29], v[28:29], v[236:237] op_sel_hi:[1,0]
	v_pk_mul_f32 v[30:31], v[30:31], v[236:237] op_sel_hi:[1,0]
	v_pk_mul_f32 v[24:25], v[24:25], v[236:237] op_sel_hi:[1,0]
	v_pk_mul_f32 v[26:27], v[26:27], v[236:237] op_sel_hi:[1,0]
	v_pk_fma_f32 v[220:221], v[108:109], v[28:29], v[100:101]
	v_pk_fma_f32 v[222:223], v[110:111], v[30:31], v[102:103]
	v_pk_fma_f32 v[224:225], v[104:105], v[24:25], v[96:97]
	v_pk_fma_f32 v[226:227], v[106:107], v[26:27], v[98:99]
	v_cndmask_b32_e64 v72, v28, v84, s[98:99]
	v_cndmask_b32_e64 v73, v29, v85, s[98:99]
	v_cndmask_b32_e64 v74, v30, v86, s[98:99]
	v_cndmask_b32_e64 v75, v31, v87, s[98:99]
	v_cndmask_b32_e64 v76, v24, v80, s[98:99]
	v_cndmask_b32_e64 v77, v25, v81, s[98:99]
	v_cndmask_b32_e64 v78, v26, v82, s[98:99]
	v_cndmask_b32_e64 v79, v27, v83, s[98:99]
	v_fmac_f32_dpp v220, v72, v116 row_ror:1 row_mask:0xf bank_mask:0xf
	v_fmac_f32_dpp v221, v73, v117 row_ror:1 row_mask:0xf bank_mask:0xf
	v_fmac_f32_dpp v222, v74, v118 row_ror:1 row_mask:0xf bank_mask:0xf
	v_fmac_f32_dpp v223, v75, v119 row_ror:1 row_mask:0xf bank_mask:0xf
	v_fmac_f32_dpp v224, v76, v112 row_ror:1 row_mask:0xf bank_mask:0xf
	v_fmac_f32_dpp v225, v77, v113 row_ror:1 row_mask:0xf bank_mask:0xf
	v_fmac_f32_dpp v226, v78, v114 row_ror:1 row_mask:0xf bank_mask:0xf
	v_fmac_f32_dpp v227, v79, v115 row_ror:1 row_mask:0xf bank_mask:0xf
	v_cndmask_b32_e64 v72, v84, v28, s[40:41]
	v_cndmask_b32_e64 v73, v85, v29, s[40:41]
	v_cndmask_b32_e64 v74, v86, v30, s[40:41]
	v_cndmask_b32_e64 v75, v87, v31, s[40:41]
	v_cndmask_b32_e64 v76, v80, v24, s[40:41]
	v_cndmask_b32_e64 v77, v81, v25, s[40:41]
	v_cndmask_b32_e64 v78, v82, v26, s[40:41]
	v_cndmask_b32_e64 v79, v83, v27, s[40:41]
	v_fmac_f32_dpp v220, v72, v124 row_ror:2 row_mask:0xf bank_mask:0xf
	v_fmac_f32_dpp v221, v73, v125 row_ror:2 row_mask:0xf bank_mask:0xf
	v_fmac_f32_dpp v222, v74, v126 row_ror:2 row_mask:0xf bank_mask:0xf
	v_fmac_f32_dpp v223, v75, v127 row_ror:2 row_mask:0xf bank_mask:0xf
	v_fmac_f32_dpp v224, v76, v120 row_ror:2 row_mask:0xf bank_mask:0xf
	v_fmac_f32_dpp v225, v77, v121 row_ror:2 row_mask:0xf bank_mask:0xf
	v_fmac_f32_dpp v226, v78, v122 row_ror:2 row_mask:0xf bank_mask:0xf
	v_fmac_f32_dpp v227, v79, v123 row_ror:2 row_mask:0xf bank_mask:0xf
	v_pk_mul_f32 v[190:191], v[220:221], s[100:101] op_sel_hi:[1,0]
	v_pk_mul_f32 v[250:251], v[222:223], s[100:101] op_sel_hi:[1,0]
	v_exp_f32_e32 v190, v190
	v_exp_f32_e32 v191, v191
	v_exp_f32_e32 v250, v250
	v_exp_f32_e32 v251, v251
	v_pk_mul_f32 v[220:221], v[220:221], v[224:225]
	v_pk_mul_f32 v[222:223], v[222:223], v[226:227]
	v_pk_add_f32 v[190:191], v[190:191], 1.0 op_sel_hi:[1,0]
	v_pk_add_f32 v[250:251], v[250:251], 1.0 op_sel_hi:[1,0]
	v_rcp_f32_e32 v190, v190
	v_rcp_f32_e32 v191, v191
	v_rcp_f32_e32 v250, v250
	v_rcp_f32_e32 v251, v251
	v_pk_mul_f32 v[220:221], v[220:221], v[190:191]
	v_pk_mul_f32 v[222:223], v[222:223], v[250:251]
	v_cvt_pk_bf16_f32 v162, v220, v221
	v_cvt_pk_bf16_f32 v163, v222, v223
	v_add_u32_e32 v243, 0xb0000, v239
	global_store_dwordx4 v243, v[160:163], s[24:25]
	v_pk_mul_f32 v[20:21], v[20:21], v[238:239] op_sel_hi:[1,0]
	v_pk_mul_f32 v[22:23], v[22:23], v[238:239] op_sel_hi:[1,0]
	v_pk_mul_f32 v[16:17], v[16:17], v[238:239] op_sel_hi:[1,0]
	v_pk_mul_f32 v[18:19], v[18:19], v[238:239] op_sel_hi:[1,0]
	v_pk_fma_f32 v[220:221], v[108:109], v[20:21], v[100:101]
	v_pk_fma_f32 v[222:223], v[110:111], v[22:23], v[102:103]
	v_pk_fma_f32 v[224:225], v[104:105], v[16:17], v[96:97]
	v_pk_fma_f32 v[226:227], v[106:107], v[18:19], v[98:99]
	v_cndmask_b32_e64 v72, v20, v28, s[98:99]
	v_cndmask_b32_e64 v73, v21, v29, s[98:99]
	v_cndmask_b32_e64 v74, v22, v30, s[98:99]
	v_cndmask_b32_e64 v75, v23, v31, s[98:99]
	v_cndmask_b32_e64 v76, v16, v24, s[98:99]
	v_cndmask_b32_e64 v77, v17, v25, s[98:99]
	v_cndmask_b32_e64 v78, v18, v26, s[98:99]
	v_cndmask_b32_e64 v79, v19, v27, s[98:99]
	v_fmac_f32_dpp v220, v72, v116 row_ror:1 row_mask:0xf bank_mask:0xf
	v_fmac_f32_dpp v221, v73, v117 row_ror:1 row_mask:0xf bank_mask:0xf
	v_fmac_f32_dpp v222, v74, v118 row_ror:1 row_mask:0xf bank_mask:0xf
	v_fmac_f32_dpp v223, v75, v119 row_ror:1 row_mask:0xf bank_mask:0xf
	v_fmac_f32_dpp v224, v76, v112 row_ror:1 row_mask:0xf bank_mask:0xf
	v_fmac_f32_dpp v225, v77, v113 row_ror:1 row_mask:0xf bank_mask:0xf
	v_fmac_f32_dpp v226, v78, v114 row_ror:1 row_mask:0xf bank_mask:0xf
	v_fmac_f32_dpp v227, v79, v115 row_ror:1 row_mask:0xf bank_mask:0xf
	v_cndmask_b32_e64 v72, v28, v20, s[40:41]
	v_cndmask_b32_e64 v73, v29, v21, s[40:41]
	v_cndmask_b32_e64 v74, v30, v22, s[40:41]
	v_cndmask_b32_e64 v75, v31, v23, s[40:41]
	v_cndmask_b32_e64 v76, v24, v16, s[40:41]
	v_cndmask_b32_e64 v77, v25, v17, s[40:41]
	v_cndmask_b32_e64 v78, v26, v18, s[40:41]
	v_cndmask_b32_e64 v79, v27, v19, s[40:41]
	v_fmac_f32_dpp v220, v72, v124 row_ror:2 row_mask:0xf bank_mask:0xf
	v_fmac_f32_dpp v221, v73, v125 row_ror:2 row_mask:0xf bank_mask:0xf
	v_fmac_f32_dpp v222, v74, v126 row_ror:2 row_mask:0xf bank_mask:0xf
	v_fmac_f32_dpp v223, v75, v127 row_ror:2 row_mask:0xf bank_mask:0xf
	v_fmac_f32_dpp v224, v76, v120 row_ror:2 row_mask:0xf bank_mask:0xf
	v_fmac_f32_dpp v225, v77, v121 row_ror:2 row_mask:0xf bank_mask:0xf
	v_fmac_f32_dpp v226, v78, v122 row_ror:2 row_mask:0xf bank_mask:0xf
	v_fmac_f32_dpp v227, v79, v123 row_ror:2 row_mask:0xf bank_mask:0xf
	v_pk_mul_f32 v[190:191], v[220:221], s[100:101] op_sel_hi:[1,0]
	v_pk_mul_f32 v[250:251], v[222:223], s[100:101] op_sel_hi:[1,0]
	v_exp_f32_e32 v190, v190
	v_exp_f32_e32 v191, v191
	v_exp_f32_e32 v250, v250
	v_exp_f32_e32 v251, v251
	v_pk_mul_f32 v[220:221], v[220:221], v[224:225]
; __device__ __forceinline__ unsigned cvt_pk_bf16(float lo, float hi) { unsigned r; asm volatile("v_cvt_pk_bf16_f32 %0, %1, %2" : "=v"(r) : "v"(lo), "v"(hi)); return r; }
; __device__ __forceinline__ float dpp_ror1(float x) { return __int_as_float(__builtin_amdgcn_update_dpp(0, __float_as_int(x), 0x121, 0xf, 0xf, false)); }
; __device__ __forceinline__ float dpp_ror2(float x) { return __int_as_float(__builtin_amdgcn_update_dpp(0, __float_as_int(x), 0x122, 0xf, 0xf, false)); }
;     __device__ __forceinline__ void operator()(const f32x4 (&acc)[2][2][4][2], const Unit& u, int wr, int wc, int fr, int fq) const {
;     ...
;                         if (ai == 1 && wr == 1) *(f32x4*)(rawh + (size_t)(u.pm * 2 + (fr - 14)) * FF2 + bj * FF + gcol + 4 * n) = x; }
;     ...
;                 for (int m = 0; m < 4; ++m) {
;                     f32x4 cur[2], h[2];
; #pragma unroll
;                     for (int bj = 0; bj < 2; ++bj) { cur[bj] = acc[ai][bj][m][n] * rs[ai][m]; f32x4 x1, x2;
; #pragma unroll
;                         for (int e = 0; e < 4; ++e) { const float c1 = dpp_ror1(cur[bj][e]), p1 = dpp_ror1(pg[bj][e]), c2 = dpp_ror2(cur[bj][e]), p2 = dpp_ror2(pg[bj][e]);
;                             x1[e] = fr >= 1 ? c1 : p1; x2[e] = fr >= 2 ? c2 : p2; }
;                         h[bj] = bb[bj] + w0[bj] * x2 + w1[bj] * x1 + w2[bj] * cur[bj]; }
;                     if (ai == 0 && wr == 0 && m == 0 && fr < 2) {
;                         *(f32x4*)(hc0 + (size_t)(u.pm * 2 + fr) * FF2 + gcol + 4 * n) = h[0]; *(f32x4*)(hc0 + (size_t)(u.pm * 2 + fr) * FF2 + FF + gcol + 4 * n) = h[1]; }
;                     f32x4 a;
; #pragma unroll
;                     for (int e = 0; e < 4; ++e) { const float g = h[0][e]; a[e] = g * __builtin_amdgcn_rcpf(1.0f + __builtin_amdgcn_exp2f(-1.4426950408889634f * g)) * h[1][e]; }
;                     const unsigned p0 = cvt_pk_bf16(a[0], a[1]), p1 = cvt_pk_bf16(a[2], a[3]);
;                     if (n == 0) { pk_lo[ai][m][0] = p0; pk_lo[ai][m][1] = p1; }
;                     else { u32x4 w; w.x = pk_lo[ai][m][0]; w.y = pk_lo[ai][m][1]; w.z = p0; w.w = p1;
;                         *(u32x4*)(act + (size_t)(u.pm * BM + ai * HALF + wr * 64 + m * 16 + fr) * FF + gcol) = w; }
	v_pk_mul_f32 v[222:223], v[222:223], v[226:227]
	v_pk_add_f32 v[190:191], v[190:191], 1.0 op_sel_hi:[1,0]
	v_pk_add_f32 v[250:251], v[250:251], 1.0 op_sel_hi:[1,0]
	v_rcp_f32_e32 v190, v190
	v_rcp_f32_e32 v191, v191
	v_rcp_f32_e32 v250, v250
	v_rcp_f32_e32 v251, v251
	v_pk_mul_f32 v[220:221], v[220:221], v[190:191]
	v_pk_mul_f32 v[222:223], v[222:223], v[250:251]
	v_cvt_pk_bf16_f32 v166, v220, v221
	v_cvt_pk_bf16_f32 v167, v222, v223
	v_add_u32_e32 v243, 0xc6000, v239
	global_store_dwordx4 v243, v[164:167], s[24:25]
	v_pk_mul_f32 v[12:13], v[12:13], v[240:241] op_sel_hi:[1,0]
	v_pk_mul_f32 v[14:15], v[14:15], v[240:241] op_sel_hi:[1,0]
	v_pk_mul_f32 v[8:9], v[8:9], v[240:241] op_sel_hi:[1,0]
	v_pk_mul_f32 v[10:11], v[10:11], v[240:241] op_sel_hi:[1,0]
	v_pk_fma_f32 v[220:221], v[108:109], v[12:13], v[100:101]
	v_pk_fma_f32 v[222:223], v[110:111], v[14:15], v[102:103]
	v_pk_fma_f32 v[224:225], v[104:105], v[8:9], v[96:97]
	v_pk_fma_f32 v[226:227], v[106:107], v[10:11], v[98:99]
	v_cndmask_b32_e64 v72, v12, v20, s[98:99]
	v_cndmask_b32_e64 v73, v13, v21, s[98:99]
	v_cndmask_b32_e64 v74, v14, v22, s[98:99]
	v_cndmask_b32_e64 v75, v15, v23, s[98:99]
	v_cndmask_b32_e64 v76, v8, v16, s[98:99]
	v_cndmask_b32_e64 v77, v9, v17, s[98:99]
	v_cndmask_b32_e64 v78, v10, v18, s[98:99]
	v_cndmask_b32_e64 v79, v11, v19, s[98:99]
	v_fmac_f32_dpp v220, v72, v116 row_ror:1 row_mask:0xf bank_mask:0xf
	v_fmac_f32_dpp v221, v73, v117 row_ror:1 row_mask:0xf bank_mask:0xf
	v_fmac_f32_dpp v222, v74, v118 row_ror:1 row_mask:0xf bank_mask:0xf
	v_fmac_f32_dpp v223, v75, v119 row_ror:1 row_mask:0xf bank_mask:0xf
	v_fmac_f32_dpp v224, v76, v112 row_ror:1 row_mask:0xf bank_mask:0xf
	v_fmac_f32_dpp v225, v77, v113 row_ror:1 row_mask:0xf bank_mask:0xf
	v_fmac_f32_dpp v226, v78, v114 row_ror:1 row_mask:0xf bank_mask:0xf
	v_fmac_f32_dpp v227, v79, v115 row_ror:1 row_mask:0xf bank_mask:0xf
	v_cndmask_b32_e64 v72, v20, v12, s[40:41]
	v_cndmask_b32_e64 v73, v21, v13, s[40:41]
	v_cndmask_b32_e64 v74, v22, v14, s[40:41]
	v_cndmask_b32_e64 v75, v23, v15, s[40:41]
	v_cndmask_b32_e64 v76, v16, v8, s[40:41]
	v_cndmask_b32_e64 v77, v17, v9, s[40:41]
	v_cndmask_b32_e64 v78, v18, v10, s[40:41]
	v_cndmask_b32_e64 v79, v19, v11, s[40:41]
	v_fmac_f32_dpp v220, v72, v124 row_ror:2 row_mask:0xf bank_mask:0xf
	v_fmac_f32_dpp v221, v73, v125 row_ror:2 row_mask:0xf bank_mask:0xf
	v_fmac_f32_dpp v222, v74, v126 row_ror:2 row_mask:0xf bank_mask:0xf
	v_fmac_f32_dpp v223, v75, v127 row_ror:2 row_mask:0xf bank_mask:0xf
	v_fmac_f32_dpp v224, v76, v120 row_ror:2 row_mask:0xf bank_mask:0xf
	v_fmac_f32_dpp v225, v77, v121 row_ror:2 row_mask:0xf bank_mask:0xf
	v_fmac_f32_dpp v226, v78, v122 row_ror:2 row_mask:0xf bank_mask:0xf
	v_fmac_f32_dpp v227, v79, v123 row_ror:2 row_mask:0xf bank_mask:0xf
	v_pk_mul_f32 v[190:191], v[220:221], s[100:101] op_sel_hi:[1,0]
	v_pk_mul_f32 v[250:251], v[222:223], s[100:101] op_sel_hi:[1,0]
	v_exp_f32_e32 v190, v190
	v_exp_f32_e32 v191, v191
	v_exp_f32_e32 v250, v250
	v_exp_f32_e32 v251, v251
	v_pk_mul_f32 v[220:221], v[220:221], v[224:225]
	v_pk_mul_f32 v[222:223], v[222:223], v[226:227]
	v_pk_add_f32 v[190:191], v[190:191], 1.0 op_sel_hi:[1,0]
	v_pk_add_f32 v[250:251], v[250:251], 1.0 op_sel_hi:[1,0]
	v_rcp_f32_e32 v190, v190
	v_rcp_f32_e32 v191, v191
	v_rcp_f32_e32 v250, v250
	v_rcp_f32_e32 v251, v251
	v_pk_mul_f32 v[220:221], v[220:221], v[190:191]
	v_pk_mul_f32 v[222:223], v[222:223], v[250:251]
	v_cvt_pk_bf16_f32 v180, v220, v221
	v_cvt_pk_bf16_f32 v181, v222, v223
	v_add_u32_e32 v243, 0xdc000, v239
	global_store_dwordx4 v243, v[178:181], s[24:25]
	v_pk_fma_f32 v[220:221], v[108:109], v[4:5], v[100:101]
	v_pk_fma_f32 v[222:223], v[110:111], v[6:7], v[102:103]
	v_pk_fma_f32 v[224:225], v[104:105], v[0:1], v[96:97]
	v_pk_fma_f32 v[226:227], v[106:107], v[2:3], v[98:99]
	v_cndmask_b32_e64 v72, v4, v12, s[98:99]
	v_cndmask_b32_e64 v73, v5, v13, s[98:99]
	v_cndmask_b32_e64 v74, v6, v14, s[98:99]
	v_cndmask_b32_e64 v75, v7, v15, s[98:99]
	v_cndmask_b32_e64 v76, v0, v8, s[98:99]
	v_cndmask_b32_e64 v77, v1, v9, s[98:99]
	v_cndmask_b32_e64 v78, v2, v10, s[98:99]
	v_cndmask_b32_e64 v79, v3, v11, s[98:99]
	v_fmac_f32_dpp v220, v72, v116 row_ror:1 row_mask:0xf bank_mask:0xf
	v_fmac_f32_dpp v221, v73, v117 row_ror:1 row_mask:0xf bank_mask:0xf
	v_fmac_f32_dpp v222, v74, v118 row_ror:1 row_mask:0xf bank_mask:0xf
	v_fmac_f32_dpp v223, v75, v119 row_ror:1 row_mask:0xf bank_mask:0xf
	v_fmac_f32_dpp v224, v76, v112 row_ror:1 row_mask:0xf bank_mask:0xf
	v_fmac_f32_dpp v225, v77, v113 row_ror:1 row_mask:0xf bank_mask:0xf
	v_fmac_f32_dpp v226, v78, v114 row_ror:1 row_mask:0xf bank_mask:0xf
	v_fmac_f32_dpp v227, v79, v115 row_ror:1 row_mask:0xf bank_mask:0xf
	v_cndmask_b32_e64 v72, v12, v4, s[40:41]
	v_cndmask_b32_e64 v73, v13, v5, s[40:41]
	v_cndmask_b32_e64 v74, v14, v6, s[40:41]
	v_cndmask_b32_e64 v75, v15, v7, s[40:41]
	v_cndmask_b32_e64 v76, v8, v0, s[40:41]
	v_cndmask_b32_e64 v77, v9, v1, s[40:41]
	v_cndmask_b32_e64 v78, v10, v2, s[40:41]
	v_cndmask_b32_e64 v79, v11, v3, s[40:41]
	v_fmac_f32_dpp v220, v72, v124 row_ror:2 row_mask:0xf bank_mask:0xf
	v_fmac_f32_dpp v221, v73, v125 row_ror:2 row_mask:0xf bank_mask:0xf
	v_fmac_f32_dpp v222, v74, v126 row_ror:2 row_mask:0xf bank_mask:0xf
	v_fmac_f32_dpp v223, v75, v127 row_ror:2 row_mask:0xf bank_mask:0xf
	v_fmac_f32_dpp v224, v76, v120 row_ror:2 row_mask:0xf bank_mask:0xf
	v_fmac_f32_dpp v225, v77, v121 row_ror:2 row_mask:0xf bank_mask:0xf
	v_fmac_f32_dpp v226, v78, v122 row_ror:2 row_mask:0xf bank_mask:0xf
	v_fmac_f32_dpp v227, v79, v123 row_ror:2 row_mask:0xf bank_mask:0xf
	v_pk_mul_f32 v[190:191], v[220:221], s[100:101] op_sel_hi:[1,0]
	v_pk_mul_f32 v[250:251], v[222:223], s[100:101] op_sel_hi:[1,0]
	v_exp_f32_e32 v190, v190
	v_exp_f32_e32 v191, v191
	v_exp_f32_e32 v250, v250
	v_exp_f32_e32 v251, v251
	v_pk_mul_f32 v[220:221], v[220:221], v[224:225]
	v_pk_mul_f32 v[222:223], v[222:223], v[226:227]
	v_pk_add_f32 v[190:191], v[190:191], 1.0 op_sel_hi:[1,0]
	v_pk_add_f32 v[250:251], v[250:251], 1.0 op_sel_hi:[1,0]
	v_rcp_f32_e32 v190, v190
	v_rcp_f32_e32 v191, v191
	v_rcp_f32_e32 v250, v250
	v_rcp_f32_e32 v251, v251
	v_pk_mul_f32 v[220:221], v[220:221], v[190:191]
	v_pk_mul_f32 v[222:223], v[222:223], v[250:251]
	v_cvt_pk_bf16_f32 v184, v220, v221
	v_cvt_pk_bf16_f32 v185, v222, v223
	v_add_u32_e32 v243, 0xf2000, v239
	global_store_dwordx4 v243, v[182:185], s[24:25]
	s_cmp_eq_u32 s79, 0
	s_cbranch_scc1 .Lp7_nored
; __device__ __forceinline__ float row_rstd(const float* slots, int row) {
;     const f32x4* s = (const f32x4*)(slots + (size_t)row * 16);
;     const f32x4 a = s[0], b = s[1], c = s[2], d = s[3];
;     const f32x4 t = (a + b) + (c + d);
;     const float ss = (t[0] + t[1]) + (t[2] + t[3]);
;     return __builtin_amdgcn_rsqf(ss * (1.0f / 1024.0f) + 1e-6f);
; }
; __device__ __forceinline__ void load_rs(const float* slots, int rowbase, int fr, int fq, float scale, float (&rs)[2][4]) {
;     float loc[2];
; #pragma unroll
;     for (int ai = 0; ai < 2; ++ai) loc[ai] = scale * row_rstd(slots, rowbase + ai * HALF + fq * 16 + fr);
; #pragma unroll
;     for (int ai = 0; ai < 2; ++ai)
; #pragma unroll
;         for (int m = 0; m < 4; ++m) rs[ai][m] = __shfl(loc[ai], m * 16 + fr);
	s_waitcnt vmcnt(4)
	v_pk_add_f32 v[62:63], v[62:63], v[54:55]
	v_pk_add_f32 v[58:59], v[58:59], v[50:51]
	v_pk_add_f32 v[60:61], v[60:61], v[52:53]
	v_pk_add_f32 v[56:57], v[56:57], v[48:49]
	v_pk_add_f32 v[52:53], v[46:47], v[38:39]
	v_pk_add_f32 v[48:49], v[42:43], v[34:35]
	v_pk_add_f32 v[54:55], v[44:45], v[36:37]
	v_pk_add_f32 v[50:51], v[40:41], v[32:33]
	v_pk_add_f32 v[62:63], v[62:63], v[52:53]
	v_pk_add_f32 v[58:59], v[58:59], v[48:49]
	v_pk_add_f32 v[60:61], v[60:61], v[54:55]
	v_pk_add_f32 v[56:57], v[56:57], v[50:51]
	v_add_f32_e32 v60, v60, v61
	v_add_f32_e32 v56, v56, v57
	v_add_f32_e32 v61, v62, v63
	v_add_f32_e32 v57, v58, v59
	v_add_f32_e32 v60, v60, v61
	v_add_f32_e32 v56, v56, v57
	v_fmamk_f32 v60, v60, 0x3a800000, v244
	v_fmamk_f32 v56, v56, 0x3a800000, v244
	v_rsq_f32_e32 v60, v60
	v_rsq_f32_e32 v56, v56
	ds_bpermute_b32 v228, v237, v60
	ds_bpermute_b32 v230, v237, v60 offset:64
	ds_bpermute_b32 v232, v237, v60 offset:128
	ds_bpermute_b32 v234, v237, v60 offset:192
	ds_bpermute_b32 v236, v237, v56
	ds_bpermute_b32 v238, v237, v56 offset:64
	ds_bpermute_b32 v240, v237, v56 offset:128
	ds_bpermute_b32 v248, v237, v56 offset:192
	s_mov_b32 s101, s10
